# v38 plus all s_setprio flips removed from the GEMM K-loops (A/B of priority hints)
# speedup vs baseline: 1.2065x; 1.0008x over previous
.LBB0_180:
	s_add_u32 s18, s50, 0xfff80080
	s_addc_u32 s19, s51, -1
	s_add_i32 s78, 0, 0x10000
	s_cmp_eq_u32 s77, 28
	s_cselect_b32 s55, s35, s19
	s_cselect_b32 s54, s73, s18
	v_add_u32_e32 v140, s78, v143
	s_cselect_b32 s19, s25, s76
	s_cselect_b32 s18, s74, s75
	s_add_i32 s80, 0, 0x14000
	ds_read_b128 v[146:149], v140
	ds_read_b128 v[150:153], v140 offset:1024
	ds_read_b128 v[154:157], v140 offset:2048
	ds_read_b128 v[168:171], v140 offset:3072
	v_add_u32_e32 v140, s80, v143
	ds_read_b128 v[172:175], v140
	ds_read_b128 v[176:179], v140 offset:1024
	ds_read_b128 v[180:183], v140 offset:2048
	ds_read_b128 v[184:187], v140 offset:3072
	v_lshl_add_u64 v[140:141], s[50:51], 0, v[138:139]
	s_add_i32 m0, s61, 0xc000
	ds_read_b128 v[188:191], v145
	ds_read_b128 v[200:203], v145 offset:1024
	ds_read_b128 v[204:207], v145 offset:2048
	ds_read_b128 v[208:211], v145 offset:3072
	ds_read_b128 v[212:215], v145 offset:4096
	ds_read_b128 v[216:219], v145 offset:5120
	ds_read_b128 v[220:223], v145 offset:6144
	ds_read_b128 v[224:227], v145 offset:7168
	global_load_lds_dwordx4 v[140:141], off
	v_lshl_add_u64 v[140:141], s[50:51], 0, v[136:137]
	s_add_i32 m0, s61, 0xe000
	s_nop 0
	global_load_lds_dwordx4 v[140:141], off
	s_waitcnt vmcnt(8)
	s_waitcnt lgkmcnt(0)
	s_barrier
	s_waitcnt lgkmcnt(0)
	v_mfma_f32_16x16x32_bf16 v[126:129], v[146:149], v[188:191], v[126:129]
	v_mfma_f32_16x16x32_bf16 v[122:125], v[154:157], v[188:191], v[122:125]
	v_mfma_f32_16x16x32_bf16 v[118:121], v[146:149], v[204:207], v[118:121]
	v_mfma_f32_16x16x32_bf16 v[110:113], v[154:157], v[204:207], v[110:113]
	v_mfma_f32_16x16x32_bf16 v[102:105], v[146:149], v[212:215], v[102:105]
	v_mfma_f32_16x16x32_bf16 v[92:95], v[154:157], v[212:215], v[92:95]
	v_mfma_f32_16x16x32_bf16 v[84:87], v[146:149], v[220:223], v[84:87]
	v_mfma_f32_16x16x32_bf16 v[76:79], v[154:157], v[220:223], v[76:79]
	v_mfma_f32_16x16x32_bf16 v[126:129], v[150:153], v[200:203], v[126:129]
	v_mfma_f32_16x16x32_bf16 v[122:125], v[168:171], v[200:203], v[122:125]
	v_mfma_f32_16x16x32_bf16 v[118:121], v[150:153], v[208:211], v[118:121]
	v_mfma_f32_16x16x32_bf16 v[110:113], v[168:171], v[208:211], v[110:113]
	v_mfma_f32_16x16x32_bf16 v[102:105], v[150:153], v[216:219], v[102:105]
	v_mfma_f32_16x16x32_bf16 v[92:95], v[168:171], v[216:219], v[92:95]
	v_mfma_f32_16x16x32_bf16 v[84:87], v[150:153], v[224:227], v[84:87]
	v_mfma_f32_16x16x32_bf16 v[76:79], v[168:171], v[224:227], v[76:79]
	v_mfma_f32_16x16x32_bf16 v[114:117], v[172:175], v[188:191], v[114:117]
	v_mfma_f32_16x16x32_bf16 v[106:109], v[180:183], v[188:191], v[106:109]
	v_mfma_f32_16x16x32_bf16 v[98:101], v[172:175], v[204:207], v[98:101]
	v_mfma_f32_16x16x32_bf16 v[88:91], v[180:183], v[204:207], v[88:91]
	v_mfma_f32_16x16x32_bf16 v[80:83], v[172:175], v[212:215], v[80:83]
	v_mfma_f32_16x16x32_bf16 v[72:75], v[180:183], v[212:215], v[72:75]
	v_mfma_f32_16x16x32_bf16 v[68:71], v[172:175], v[220:223], v[68:71]
	v_mfma_f32_16x16x32_bf16 v[64:67], v[180:183], v[220:223], v[64:67]
	v_mfma_f32_16x16x32_bf16 v[114:117], v[176:179], v[200:203], v[114:117]
	v_mfma_f32_16x16x32_bf16 v[106:109], v[184:187], v[200:203], v[106:109]
	v_mfma_f32_16x16x32_bf16 v[98:101], v[176:179], v[208:211], v[98:101]
	v_mfma_f32_16x16x32_bf16 v[88:91], v[184:187], v[208:211], v[88:91]
	v_mfma_f32_16x16x32_bf16 v[80:83], v[176:179], v[216:219], v[80:83]
	v_mfma_f32_16x16x32_bf16 v[72:75], v[184:187], v[216:219], v[72:75]
	v_mfma_f32_16x16x32_bf16 v[68:71], v[176:179], v[224:227], v[68:71]
	v_mfma_f32_16x16x32_bf16 v[64:67], v[184:187], v[224:227], v[64:67]
	s_barrier
	s_add_i32 s78, s78, s60
	v_lshl_add_u64 v[140:141], s[18:19], 0, v[96:97]
	s_mov_b32 m0, s78
	ds_read_b128 v[188:191], v145 offset:16384
	ds_read_b128 v[200:203], v145 offset:17408
	ds_read_b128 v[204:207], v145 offset:18432
	ds_read_b128 v[208:211], v145 offset:19456
	ds_read_b128 v[212:215], v145 offset:20480
	ds_read_b128 v[216:219], v145 offset:21504
	ds_read_b128 v[220:223], v145 offset:22528
	ds_read_b128 v[224:227], v145 offset:23552
	global_load_lds_dwordx4 v[140:141], off
	s_add_i32 m0, s78, 0x2000
	s_add_u32 s78, s18, 0x80000
	v_lshl_add_u64 v[192:193], s[18:19], 0, v[130:131]
	s_addc_u32 s79, s19, 0
	s_add_i32 s80, s80, s60
	global_load_lds_dwordx4 v[192:193], off
	v_lshl_add_u64 v[196:197], s[78:79], 0, v[96:97]
	s_mov_b32 m0, s80
	v_lshl_add_u64 v[198:199], s[54:55], 0, v[132:133]
	global_load_lds_dwordx4 v[196:197], off
	v_lshl_add_u64 v[196:197], s[78:79], 0, v[130:131]
	s_add_i32 m0, s80, 0x2000
	s_nop 0
	global_load_lds_dwordx4 v[196:197], off
	v_lshl_add_u64 v[196:197], s[54:55], 0, v[134:135]
	s_mov_b32 m0, s61
	s_nop 0
	global_load_lds_dwordx4 v[196:197], off
	s_mov_b32 m0, s65
	s_nop 0
	global_load_lds_dwordx4 v[198:199], off
	s_waitcnt vmcnt(8)
	s_waitcnt lgkmcnt(0)
	s_barrier
	s_waitcnt lgkmcnt(0)
	v_mfma_f32_16x16x32_bf16 v[60:63], v[146:149], v[188:191], v[60:63]
	v_mfma_f32_16x16x32_bf16 v[56:59], v[154:157], v[188:191], v[56:59]
	v_mfma_f32_16x16x32_bf16 v[52:55], v[146:149], v[204:207], v[52:55]
	v_mfma_f32_16x16x32_bf16 v[44:47], v[154:157], v[204:207], v[44:47]
	v_mfma_f32_16x16x32_bf16 v[36:39], v[146:149], v[212:215], v[36:39]
	v_mfma_f32_16x16x32_bf16 v[28:31], v[154:157], v[212:215], v[28:31]
	v_mfma_f32_16x16x32_bf16 v[20:23], v[146:149], v[220:223], v[20:23]
	v_mfma_f32_16x16x32_bf16 v[12:15], v[154:157], v[220:223], v[12:15]
	v_mfma_f32_16x16x32_bf16 v[60:63], v[150:153], v[200:203], v[60:63]
	v_mfma_f32_16x16x32_bf16 v[56:59], v[168:171], v[200:203], v[56:59]
	v_mfma_f32_16x16x32_bf16 v[52:55], v[150:153], v[208:211], v[52:55]
	v_mfma_f32_16x16x32_bf16 v[44:47], v[168:171], v[208:211], v[44:47]
	v_mfma_f32_16x16x32_bf16 v[36:39], v[150:153], v[216:219], v[36:39]
	v_mfma_f32_16x16x32_bf16 v[28:31], v[168:171], v[216:219], v[28:31]
	v_mfma_f32_16x16x32_bf16 v[20:23], v[150:153], v[224:227], v[20:23]
	v_mfma_f32_16x16x32_bf16 v[12:15], v[168:171], v[224:227], v[12:15]
	v_mfma_f32_16x16x32_bf16 v[48:51], v[172:175], v[188:191], v[48:51]
	v_mfma_f32_16x16x32_bf16 v[40:43], v[180:183], v[188:191], v[40:43]
	v_mfma_f32_16x16x32_bf16 v[32:35], v[172:175], v[204:207], v[32:35]
	v_mfma_f32_16x16x32_bf16 v[24:27], v[180:183], v[204:207], v[24:27]
	v_mfma_f32_16x16x32_bf16 v[16:19], v[172:175], v[212:215], v[16:19]
	v_mfma_f32_16x16x32_bf16 v[8:11], v[180:183], v[212:215], v[8:11]
	v_mfma_f32_16x16x32_bf16 v[4:7], v[172:175], v[220:223], v[4:7]
	v_mfma_f32_16x16x32_bf16 v[0:3], v[180:183], v[220:223], v[0:3]
	v_mfma_f32_16x16x32_bf16 v[48:51], v[176:179], v[200:203], v[48:51]
	v_mfma_f32_16x16x32_bf16 v[40:43], v[184:187], v[200:203], v[40:43]
	v_mfma_f32_16x16x32_bf16 v[32:35], v[176:179], v[208:211], v[32:35]
	v_mfma_f32_16x16x32_bf16 v[24:27], v[184:187], v[208:211], v[24:27]
	v_mfma_f32_16x16x32_bf16 v[16:19], v[176:179], v[216:219], v[16:19]
	v_mfma_f32_16x16x32_bf16 v[8:11], v[184:187], v[216:219], v[8:11]
	v_mfma_f32_16x16x32_bf16 v[4:7], v[176:179], v[224:227], v[4:7]
	v_mfma_f32_16x16x32_bf16 v[0:3], v[184:187], v[224:227], v[0:3]
	s_barrier
	s_add_i32 s78, 0, 0x18000
	s_add_i32 s79, 0, 0x1c000
	v_add_u32_e32 v168, s78, v143
	v_add_u32_e32 v184, s79, v143
	ds_read_b128 v[146:149], v168
	ds_read_b128 v[150:153], v168 offset:1024
	ds_read_b128 v[154:157], v168 offset:2048
	ds_read_b128 v[168:171], v168 offset:3072
	ds_read_b128 v[172:175], v184
	ds_read_b128 v[176:179], v184 offset:1024
	ds_read_b128 v[180:183], v184 offset:2048
	ds_read_b128 v[184:187], v184 offset:3072
	s_add_u32 s54, s54, 0x80000
	s_addc_u32 s55, s55, 0
	s_mov_b32 m0, s66
	v_lshl_add_u64 v[228:229], s[54:55], 0, v[134:135]
	ds_read_b128 v[188:191], v145 offset:32768
	ds_read_b128 v[200:203], v145 offset:33792
	ds_read_b128 v[204:207], v145 offset:34816
	ds_read_b128 v[208:211], v145 offset:35840
	ds_read_b128 v[212:215], v145 offset:36864
	ds_read_b128 v[216:219], v145 offset:37888
	ds_read_b128 v[220:223], v145 offset:38912
	ds_read_b128 v[224:227], v145 offset:39936
	global_load_lds_dwordx4 v[228:229], off
	v_lshl_add_u64 v[228:229], s[54:55], 0, v[132:133]
	s_mov_b32 m0, s67
	s_nop 0
	global_load_lds_dwordx4 v[228:229], off
	s_waitcnt vmcnt(8)
	s_waitcnt lgkmcnt(0)
	s_barrier
	s_waitcnt lgkmcnt(0)
	v_mfma_f32_16x16x32_bf16 v[126:129], v[146:149], v[188:191], v[126:129]
	v_mfma_f32_16x16x32_bf16 v[122:125], v[154:157], v[188:191], v[122:125]
	v_mfma_f32_16x16x32_bf16 v[118:121], v[146:149], v[204:207], v[118:121]
	v_mfma_f32_16x16x32_bf16 v[110:113], v[154:157], v[204:207], v[110:113]
	v_mfma_f32_16x16x32_bf16 v[102:105], v[146:149], v[212:215], v[102:105]
	v_mfma_f32_16x16x32_bf16 v[92:95], v[154:157], v[212:215], v[92:95]
	v_mfma_f32_16x16x32_bf16 v[84:87], v[146:149], v[220:223], v[84:87]
	v_mfma_f32_16x16x32_bf16 v[76:79], v[154:157], v[220:223], v[76:79]
	v_mfma_f32_16x16x32_bf16 v[126:129], v[150:153], v[200:203], v[126:129]
	v_mfma_f32_16x16x32_bf16 v[122:125], v[168:171], v[200:203], v[122:125]
	v_mfma_f32_16x16x32_bf16 v[118:121], v[150:153], v[208:211], v[118:121]
	v_mfma_f32_16x16x32_bf16 v[110:113], v[168:171], v[208:211], v[110:113]
	v_mfma_f32_16x16x32_bf16 v[102:105], v[150:153], v[216:219], v[102:105]
	v_mfma_f32_16x16x32_bf16 v[92:95], v[168:171], v[216:219], v[92:95]
	v_mfma_f32_16x16x32_bf16 v[84:87], v[150:153], v[224:227], v[84:87]
	v_mfma_f32_16x16x32_bf16 v[76:79], v[168:171], v[224:227], v[76:79]
	v_mfma_f32_16x16x32_bf16 v[114:117], v[172:175], v[188:191], v[114:117]
	v_mfma_f32_16x16x32_bf16 v[106:109], v[180:183], v[188:191], v[106:109]
	v_mfma_f32_16x16x32_bf16 v[98:101], v[172:175], v[204:207], v[98:101]
	v_mfma_f32_16x16x32_bf16 v[88:91], v[180:183], v[204:207], v[88:91]
	v_mfma_f32_16x16x32_bf16 v[80:83], v[172:175], v[212:215], v[80:83]
	v_mfma_f32_16x16x32_bf16 v[72:75], v[180:183], v[212:215], v[72:75]
	v_mfma_f32_16x16x32_bf16 v[68:71], v[172:175], v[220:223], v[68:71]
	v_mfma_f32_16x16x32_bf16 v[64:67], v[180:183], v[220:223], v[64:67]
	v_mfma_f32_16x16x32_bf16 v[114:117], v[176:179], v[200:203], v[114:117]
	v_mfma_f32_16x16x32_bf16 v[106:109], v[184:187], v[200:203], v[106:109]
	v_mfma_f32_16x16x32_bf16 v[98:101], v[176:179], v[208:211], v[98:101]
	v_mfma_f32_16x16x32_bf16 v[88:91], v[184:187], v[208:211], v[88:91]
	v_mfma_f32_16x16x32_bf16 v[80:83], v[176:179], v[216:219], v[80:83]
	v_mfma_f32_16x16x32_bf16 v[72:75], v[184:187], v[216:219], v[72:75]
	v_mfma_f32_16x16x32_bf16 v[68:71], v[176:179], v[224:227], v[68:71]
	v_mfma_f32_16x16x32_bf16 v[64:67], v[184:187], v[224:227], v[64:67]
	s_barrier
	s_add_i32 s54, s78, s60
	v_lshl_add_u64 v[140:141], v[140:141], 0, s[30:31]
	s_mov_b32 m0, s54
	ds_read_b128 v[188:191], v145 offset:49152
	ds_read_b128 v[200:203], v145 offset:50176
	ds_read_b128 v[204:207], v145 offset:51200
	ds_read_b128 v[208:211], v145 offset:52224
	ds_read_b128 v[212:215], v145 offset:53248
	ds_read_b128 v[216:219], v145 offset:54272
	ds_read_b128 v[220:223], v145 offset:55296
	ds_read_b128 v[224:227], v145 offset:56320
	global_load_lds_dwordx4 v[140:141], off
	s_add_i32 m0, s54, 0x2000
	s_add_u32 s18, s18, 0x80080
	v_lshl_add_u64 v[140:141], v[192:193], 0, s[30:31]
	s_addc_u32 s19, s19, 0
	s_add_i32 s54, s79, s60
	global_load_lds_dwordx4 v[140:141], off
	v_lshl_add_u64 v[140:141], s[18:19], 0, v[96:97]
	s_mov_b32 m0, s54
	s_nop 0
	global_load_lds_dwordx4 v[140:141], off
	v_lshl_add_u64 v[140:141], s[18:19], 0, v[130:131]
	s_add_i32 m0, s54, 0x2000
	s_nop 0
	global_load_lds_dwordx4 v[140:141], off
	v_lshl_add_u64 v[140:141], v[196:197], 0, s[30:31]
	s_mov_b32 m0, s68
	s_nop 0
	global_load_lds_dwordx4 v[140:141], off
	v_lshl_add_u64 v[140:141], v[198:199], 0, s[30:31]
	s_mov_b32 m0, s69
	s_nop 0
	global_load_lds_dwordx4 v[140:141], off
	s_waitcnt vmcnt(8)
	s_waitcnt lgkmcnt(0)
	s_barrier
	s_waitcnt lgkmcnt(0)
	v_mfma_f32_16x16x32_bf16 v[60:63], v[146:149], v[188:191], v[60:63]
	v_mfma_f32_16x16x32_bf16 v[56:59], v[154:157], v[188:191], v[56:59]
	v_mfma_f32_16x16x32_bf16 v[52:55], v[146:149], v[204:207], v[52:55]
	v_mfma_f32_16x16x32_bf16 v[44:47], v[154:157], v[204:207], v[44:47]
	v_mfma_f32_16x16x32_bf16 v[36:39], v[146:149], v[212:215], v[36:39]
	v_mfma_f32_16x16x32_bf16 v[28:31], v[154:157], v[212:215], v[28:31]
	v_mfma_f32_16x16x32_bf16 v[20:23], v[146:149], v[220:223], v[20:23]
	v_mfma_f32_16x16x32_bf16 v[12:15], v[154:157], v[220:223], v[12:15]
	v_mfma_f32_16x16x32_bf16 v[60:63], v[150:153], v[200:203], v[60:63]
	v_mfma_f32_16x16x32_bf16 v[56:59], v[168:171], v[200:203], v[56:59]
	v_mfma_f32_16x16x32_bf16 v[52:55], v[150:153], v[208:211], v[52:55]
	v_mfma_f32_16x16x32_bf16 v[44:47], v[168:171], v[208:211], v[44:47]
	v_mfma_f32_16x16x32_bf16 v[36:39], v[150:153], v[216:219], v[36:39]
	v_mfma_f32_16x16x32_bf16 v[28:31], v[168:171], v[216:219], v[28:31]
	v_mfma_f32_16x16x32_bf16 v[20:23], v[150:153], v[224:227], v[20:23]
	v_mfma_f32_16x16x32_bf16 v[12:15], v[168:171], v[224:227], v[12:15]
	v_mfma_f32_16x16x32_bf16 v[48:51], v[172:175], v[188:191], v[48:51]
	v_mfma_f32_16x16x32_bf16 v[40:43], v[180:183], v[188:191], v[40:43]
	v_mfma_f32_16x16x32_bf16 v[32:35], v[172:175], v[204:207], v[32:35]
	v_mfma_f32_16x16x32_bf16 v[24:27], v[180:183], v[204:207], v[24:27]
	v_mfma_f32_16x16x32_bf16 v[16:19], v[172:175], v[212:215], v[16:19]
	v_mfma_f32_16x16x32_bf16 v[8:11], v[180:183], v[212:215], v[8:11]
	v_mfma_f32_16x16x32_bf16 v[4:7], v[172:175], v[220:223], v[4:7]
	v_mfma_f32_16x16x32_bf16 v[0:3], v[180:183], v[220:223], v[0:3]
	v_mfma_f32_16x16x32_bf16 v[48:51], v[176:179], v[200:203], v[48:51]
	v_mfma_f32_16x16x32_bf16 v[40:43], v[184:187], v[200:203], v[40:43]
	v_mfma_f32_16x16x32_bf16 v[32:35], v[176:179], v[208:211], v[32:35]
	v_mfma_f32_16x16x32_bf16 v[24:27], v[184:187], v[208:211], v[24:27]
	v_mfma_f32_16x16x32_bf16 v[16:19], v[176:179], v[216:219], v[16:19]
	v_mfma_f32_16x16x32_bf16 v[8:11], v[184:187], v[216:219], v[8:11]
	v_mfma_f32_16x16x32_bf16 v[4:7], v[176:179], v[224:227], v[4:7]
	v_mfma_f32_16x16x32_bf16 v[0:3], v[184:187], v[224:227], v[0:3]
	s_barrier
	s_add_i32 s77, s77, 2
	s_add_u32 s75, s75, 0x100
	s_addc_u32 s76, s76, 0
	s_add_u32 s50, s50, 0x100
	s_addc_u32 s51, s51, 0
	s_cmp_gt_u32 s77, 29
	s_cbranch_scc0 .LBB0_180
	s_and_b64 vcc, exec, s[22:23]
	s_cbranch_vccz .LBB0_183
	s_barrier

.LBB0_203:
	s_add_u32 s18, s36, 0xfff80080
	s_addc_u32 s19, s37, -1
	s_add_i32 s83, 0, 0x10000
	s_cmp_eq_u32 s82, 28
	s_cselect_b32 vcc_hi, s57, s19
	s_cselect_b32 vcc_lo, s61, s18
	v_add_u32_e32 v96, s83, v151
	s_cselect_b32 s19, s55, s81
	s_cselect_b32 s18, s79, s80
	s_add_i32 s86, 0, 0x14000
	ds_read_b128 v[146:149], v96
	ds_read_b128 v[168:171], v96 offset:1024
	ds_read_b128 v[172:175], v96 offset:2048
	ds_read_b128 v[176:179], v96 offset:3072
	v_add_u32_e32 v96, s86, v151
	ds_read_b128 v[180:183], v96
	ds_read_b128 v[184:187], v96 offset:1024
	ds_read_b128 v[188:191], v96 offset:2048
	ds_read_b128 v[200:203], v96 offset:3072
	v_lshl_add_u64 v[156:157], s[36:37], 0, v[144:145]
	s_add_i32 m0, s71, 0xc000
	ds_read_b128 v[204:207], v155
	ds_read_b128 v[208:211], v155 offset:1024
	ds_read_b128 v[212:215], v155 offset:2048
	ds_read_b128 v[216:219], v155 offset:3072
	ds_read_b128 v[220:223], v155 offset:4096
	ds_read_b128 v[224:227], v155 offset:5120
	ds_read_b128 v[228:231], v155 offset:6144
	ds_read_b128 v[232:235], v155 offset:7168
	global_load_lds_dwordx4 v[156:157], off
	v_lshl_add_u64 v[156:157], s[36:37], 0, v[142:143]
	s_add_i32 m0, s71, 0xe000
	s_nop 0
	global_load_lds_dwordx4 v[156:157], off
	s_waitcnt vmcnt(8)
	s_waitcnt lgkmcnt(0)
	s_barrier
	s_waitcnt lgkmcnt(0)
	v_mfma_f32_16x16x32_bf16 v[60:63], v[146:149], v[204:207], v[60:63]
	v_mfma_f32_16x16x32_bf16 v[56:59], v[172:175], v[204:207], v[56:59]
	v_mfma_f32_16x16x32_bf16 v[52:55], v[146:149], v[212:215], v[52:55]
	v_mfma_f32_16x16x32_bf16 v[48:51], v[172:175], v[212:215], v[48:51]
	v_mfma_f32_16x16x32_bf16 v[44:47], v[146:149], v[220:223], v[44:47]
	v_mfma_f32_16x16x32_bf16 v[40:43], v[172:175], v[220:223], v[40:43]
	v_mfma_f32_16x16x32_bf16 v[36:39], v[146:149], v[228:231], v[36:39]
	v_mfma_f32_16x16x32_bf16 v[32:35], v[172:175], v[228:231], v[32:35]
	v_mfma_f32_16x16x32_bf16 v[60:63], v[168:171], v[208:211], v[60:63]
	v_mfma_f32_16x16x32_bf16 v[56:59], v[176:179], v[208:211], v[56:59]
	v_mfma_f32_16x16x32_bf16 v[52:55], v[168:171], v[216:219], v[52:55]
	v_mfma_f32_16x16x32_bf16 v[48:51], v[176:179], v[216:219], v[48:51]
	v_mfma_f32_16x16x32_bf16 v[44:47], v[168:171], v[224:227], v[44:47]
	v_mfma_f32_16x16x32_bf16 v[40:43], v[176:179], v[224:227], v[40:43]
	v_mfma_f32_16x16x32_bf16 v[36:39], v[168:171], v[232:235], v[36:39]
	v_mfma_f32_16x16x32_bf16 v[32:35], v[176:179], v[232:235], v[32:35]
	v_mfma_f32_16x16x32_bf16 v[126:129], v[180:183], v[204:207], v[126:129]
	v_mfma_f32_16x16x32_bf16 v[122:125], v[188:191], v[204:207], v[122:125]
	v_mfma_f32_16x16x32_bf16 v[118:121], v[180:183], v[212:215], v[118:121]
	v_mfma_f32_16x16x32_bf16 v[114:117], v[188:191], v[212:215], v[114:117]
	v_mfma_f32_16x16x32_bf16 v[110:113], v[180:183], v[220:223], v[110:113]
	v_mfma_f32_16x16x32_bf16 v[106:109], v[188:191], v[220:223], v[106:109]
	v_mfma_f32_16x16x32_bf16 v[102:105], v[180:183], v[228:231], v[102:105]
	v_mfma_f32_16x16x32_bf16 v[98:101], v[188:191], v[228:231], v[98:101]
	v_mfma_f32_16x16x32_bf16 v[126:129], v[184:187], v[208:211], v[126:129]
	v_mfma_f32_16x16x32_bf16 v[122:125], v[200:203], v[208:211], v[122:125]
	v_mfma_f32_16x16x32_bf16 v[118:121], v[184:187], v[216:219], v[118:121]
	v_mfma_f32_16x16x32_bf16 v[114:117], v[200:203], v[216:219], v[114:117]
	v_mfma_f32_16x16x32_bf16 v[110:113], v[184:187], v[224:227], v[110:113]
	v_mfma_f32_16x16x32_bf16 v[106:109], v[200:203], v[224:227], v[106:109]
	v_mfma_f32_16x16x32_bf16 v[102:105], v[184:187], v[232:235], v[102:105]
	v_mfma_f32_16x16x32_bf16 v[98:101], v[200:203], v[232:235], v[98:101]
	s_barrier
	s_add_i32 s83, s83, s70
	v_lshl_add_u64 v[156:157], s[18:19], 0, v[134:135]
	s_mov_b32 m0, s83
	ds_read_b128 v[204:207], v155 offset:16384
	ds_read_b128 v[208:211], v155 offset:17408
	ds_read_b128 v[212:215], v155 offset:18432
	ds_read_b128 v[216:219], v155 offset:19456
	ds_read_b128 v[220:223], v155 offset:20480
	ds_read_b128 v[224:227], v155 offset:21504
	ds_read_b128 v[228:231], v155 offset:22528
	ds_read_b128 v[232:235], v155 offset:23552
	global_load_lds_dwordx4 v[156:157], off
	s_add_i32 m0, s83, 0x2000
	s_add_u32 s84, s18, 0x80000
	v_lshl_add_u64 v[192:193], s[18:19], 0, v[130:131]
	s_addc_u32 s85, s19, 0
	s_add_i32 s83, s86, s70
	global_load_lds_dwordx4 v[192:193], off
	v_lshl_add_u64 v[196:197], s[84:85], 0, v[134:135]
	s_mov_b32 m0, s83
	v_lshl_add_u64 v[198:199], vcc, 0, v[132:133]
	global_load_lds_dwordx4 v[196:197], off
	v_lshl_add_u64 v[196:197], s[84:85], 0, v[130:131]
	s_add_i32 m0, s83, 0x2000
	s_nop 0
	global_load_lds_dwordx4 v[196:197], off
	v_lshl_add_u64 v[196:197], vcc, 0, v[136:137]
	s_mov_b32 m0, s71
	s_nop 0
	global_load_lds_dwordx4 v[196:197], off
	s_mov_b32 m0, s72
	s_nop 0
	global_load_lds_dwordx4 v[198:199], off
	s_waitcnt vmcnt(8)
	s_waitcnt lgkmcnt(0)
	s_barrier
	s_waitcnt lgkmcnt(0)
	v_mfma_f32_16x16x32_bf16 v[28:31], v[146:149], v[204:207], v[28:31]
	v_mfma_f32_16x16x32_bf16 v[24:27], v[172:175], v[204:207], v[24:27]
	v_mfma_f32_16x16x32_bf16 v[20:23], v[146:149], v[212:215], v[20:23]
	v_mfma_f32_16x16x32_bf16 v[16:19], v[172:175], v[212:215], v[16:19]
	v_mfma_f32_16x16x32_bf16 v[12:15], v[146:149], v[220:223], v[12:15]
	v_mfma_f32_16x16x32_bf16 v[8:11], v[172:175], v[220:223], v[8:11]
	v_mfma_f32_16x16x32_bf16 v[4:7], v[146:149], v[228:231], v[4:7]
	v_mfma_f32_16x16x32_bf16 v[0:3], v[172:175], v[228:231], v[0:3]
	v_mfma_f32_16x16x32_bf16 v[28:31], v[168:171], v[208:211], v[28:31]
	v_mfma_f32_16x16x32_bf16 v[24:27], v[176:179], v[208:211], v[24:27]
	v_mfma_f32_16x16x32_bf16 v[20:23], v[168:171], v[216:219], v[20:23]
	v_mfma_f32_16x16x32_bf16 v[16:19], v[176:179], v[216:219], v[16:19]
	v_mfma_f32_16x16x32_bf16 v[12:15], v[168:171], v[224:227], v[12:15]
	v_mfma_f32_16x16x32_bf16 v[8:11], v[176:179], v[224:227], v[8:11]
	v_mfma_f32_16x16x32_bf16 v[4:7], v[168:171], v[232:235], v[4:7]
	v_mfma_f32_16x16x32_bf16 v[0:3], v[176:179], v[232:235], v[0:3]
	v_mfma_f32_16x16x32_bf16 v[92:95], v[180:183], v[204:207], v[92:95]
	v_mfma_f32_16x16x32_bf16 v[88:91], v[188:191], v[204:207], v[88:91]
	v_mfma_f32_16x16x32_bf16 v[84:87], v[180:183], v[212:215], v[84:87]
	v_mfma_f32_16x16x32_bf16 v[80:83], v[188:191], v[212:215], v[80:83]
	v_mfma_f32_16x16x32_bf16 v[76:79], v[180:183], v[220:223], v[76:79]
	v_mfma_f32_16x16x32_bf16 v[72:75], v[188:191], v[220:223], v[72:75]
	v_mfma_f32_16x16x32_bf16 v[68:71], v[180:183], v[228:231], v[68:71]
	v_mfma_f32_16x16x32_bf16 v[64:67], v[188:191], v[228:231], v[64:67]
	v_mfma_f32_16x16x32_bf16 v[92:95], v[184:187], v[208:211], v[92:95]
	v_mfma_f32_16x16x32_bf16 v[88:91], v[200:203], v[208:211], v[88:91]
	v_mfma_f32_16x16x32_bf16 v[84:87], v[184:187], v[216:219], v[84:87]
	v_mfma_f32_16x16x32_bf16 v[80:83], v[200:203], v[216:219], v[80:83]
	v_mfma_f32_16x16x32_bf16 v[76:79], v[184:187], v[224:227], v[76:79]
	v_mfma_f32_16x16x32_bf16 v[72:75], v[200:203], v[224:227], v[72:75]
	v_mfma_f32_16x16x32_bf16 v[68:71], v[184:187], v[232:235], v[68:71]
	v_mfma_f32_16x16x32_bf16 v[64:67], v[200:203], v[232:235], v[64:67]
	s_barrier
	s_add_i32 s83, 0, 0x18000
	v_add_u32_e32 v96, s83, v151
	s_add_i32 s86, 0, 0x1c000
	ds_read_b128 v[146:149], v96
	ds_read_b128 v[168:171], v96 offset:1024
	ds_read_b128 v[172:175], v96 offset:2048
	ds_read_b128 v[176:179], v96 offset:3072
	v_add_u32_e32 v96, s86, v151
	ds_read_b128 v[180:183], v96
	ds_read_b128 v[184:187], v96 offset:1024
	ds_read_b128 v[188:191], v96 offset:2048
	ds_read_b128 v[200:203], v96 offset:3072
	s_add_u32 s84, vcc_lo, 0x80000
	s_addc_u32 s85, vcc_hi, 0
	s_mov_b32 m0, s73
	v_lshl_add_u64 v[236:237], s[84:85], 0, v[136:137]
	ds_read_b128 v[204:207], v155 offset:32768
	ds_read_b128 v[208:211], v155 offset:33792
	ds_read_b128 v[212:215], v155 offset:34816
	ds_read_b128 v[216:219], v155 offset:35840
	ds_read_b128 v[220:223], v155 offset:36864
	ds_read_b128 v[224:227], v155 offset:37888
	ds_read_b128 v[228:231], v155 offset:38912
	ds_read_b128 v[232:235], v155 offset:39936
	global_load_lds_dwordx4 v[236:237], off
	v_lshl_add_u64 v[236:237], s[84:85], 0, v[132:133]
	s_mov_b32 m0, s74
	s_nop 0
	global_load_lds_dwordx4 v[236:237], off
	s_waitcnt vmcnt(8)
	s_waitcnt lgkmcnt(0)
	s_barrier
	s_waitcnt lgkmcnt(0)
	v_mfma_f32_16x16x32_bf16 v[60:63], v[146:149], v[204:207], v[60:63]
	v_mfma_f32_16x16x32_bf16 v[56:59], v[172:175], v[204:207], v[56:59]
	v_mfma_f32_16x16x32_bf16 v[52:55], v[146:149], v[212:215], v[52:55]
	v_mfma_f32_16x16x32_bf16 v[48:51], v[172:175], v[212:215], v[48:51]
	v_mfma_f32_16x16x32_bf16 v[44:47], v[146:149], v[220:223], v[44:47]
	v_mfma_f32_16x16x32_bf16 v[40:43], v[172:175], v[220:223], v[40:43]
	v_mfma_f32_16x16x32_bf16 v[36:39], v[146:149], v[228:231], v[36:39]
	v_mfma_f32_16x16x32_bf16 v[32:35], v[172:175], v[228:231], v[32:35]
	v_mfma_f32_16x16x32_bf16 v[60:63], v[168:171], v[208:211], v[60:63]
	v_mfma_f32_16x16x32_bf16 v[56:59], v[176:179], v[208:211], v[56:59]
	v_mfma_f32_16x16x32_bf16 v[52:55], v[168:171], v[216:219], v[52:55]
	v_mfma_f32_16x16x32_bf16 v[48:51], v[176:179], v[216:219], v[48:51]
	v_mfma_f32_16x16x32_bf16 v[44:47], v[168:171], v[224:227], v[44:47]
	v_mfma_f32_16x16x32_bf16 v[40:43], v[176:179], v[224:227], v[40:43]
	v_mfma_f32_16x16x32_bf16 v[36:39], v[168:171], v[232:235], v[36:39]
	v_mfma_f32_16x16x32_bf16 v[32:35], v[176:179], v[232:235], v[32:35]
	v_mfma_f32_16x16x32_bf16 v[126:129], v[180:183], v[204:207], v[126:129]
	v_mfma_f32_16x16x32_bf16 v[122:125], v[188:191], v[204:207], v[122:125]
	v_mfma_f32_16x16x32_bf16 v[118:121], v[180:183], v[212:215], v[118:121]
	v_mfma_f32_16x16x32_bf16 v[114:117], v[188:191], v[212:215], v[114:117]
	v_mfma_f32_16x16x32_bf16 v[110:113], v[180:183], v[220:223], v[110:113]
	v_mfma_f32_16x16x32_bf16 v[106:109], v[188:191], v[220:223], v[106:109]
	v_mfma_f32_16x16x32_bf16 v[102:105], v[180:183], v[228:231], v[102:105]
	v_mfma_f32_16x16x32_bf16 v[98:101], v[188:191], v[228:231], v[98:101]
	v_mfma_f32_16x16x32_bf16 v[126:129], v[184:187], v[208:211], v[126:129]
	v_mfma_f32_16x16x32_bf16 v[122:125], v[200:203], v[208:211], v[122:125]
	v_mfma_f32_16x16x32_bf16 v[118:121], v[184:187], v[216:219], v[118:121]
	v_mfma_f32_16x16x32_bf16 v[114:117], v[200:203], v[216:219], v[114:117]
	v_mfma_f32_16x16x32_bf16 v[110:113], v[184:187], v[224:227], v[110:113]
	v_mfma_f32_16x16x32_bf16 v[106:109], v[200:203], v[224:227], v[106:109]
	v_mfma_f32_16x16x32_bf16 v[102:105], v[184:187], v[232:235], v[102:105]
	v_mfma_f32_16x16x32_bf16 v[98:101], v[200:203], v[232:235], v[98:101]
	s_barrier
	s_add_i32 s83, s83, s70
	v_lshl_add_u64 v[156:157], v[156:157], 0, s[30:31]
	s_mov_b32 m0, s83
	ds_read_b128 v[204:207], v155 offset:49152
	ds_read_b128 v[208:211], v155 offset:50176
	ds_read_b128 v[212:215], v155 offset:51200
	ds_read_b128 v[216:219], v155 offset:52224
	ds_read_b128 v[220:223], v155 offset:53248
	ds_read_b128 v[224:227], v155 offset:54272
	ds_read_b128 v[228:231], v155 offset:55296
	ds_read_b128 v[232:235], v155 offset:56320
	global_load_lds_dwordx4 v[156:157], off
	s_add_i32 m0, s83, 0x2000
	s_add_u32 s18, s18, 0x80080
	v_lshl_add_u64 v[156:157], v[192:193], 0, s[30:31]
	s_addc_u32 s19, s19, 0
	s_add_i32 s83, s86, s70
	global_load_lds_dwordx4 v[156:157], off
	v_lshl_add_u64 v[156:157], s[18:19], 0, v[134:135]
	s_mov_b32 m0, s83
	s_nop 0
	global_load_lds_dwordx4 v[156:157], off
	v_lshl_add_u64 v[156:157], s[18:19], 0, v[130:131]
	s_add_i32 m0, s83, 0x2000
	s_nop 0
	global_load_lds_dwordx4 v[156:157], off
	v_lshl_add_u64 v[156:157], v[196:197], 0, s[30:31]
	s_mov_b32 m0, s75
	s_nop 0
	global_load_lds_dwordx4 v[156:157], off
	v_lshl_add_u64 v[156:157], v[198:199], 0, s[30:31]
	s_mov_b32 m0, s76
	s_nop 0
	global_load_lds_dwordx4 v[156:157], off
	s_waitcnt vmcnt(8)
	s_waitcnt lgkmcnt(0)
	s_barrier
	s_waitcnt lgkmcnt(0)
	v_mfma_f32_16x16x32_bf16 v[28:31], v[146:149], v[204:207], v[28:31]
	v_mfma_f32_16x16x32_bf16 v[24:27], v[172:175], v[204:207], v[24:27]
	v_mfma_f32_16x16x32_bf16 v[20:23], v[146:149], v[212:215], v[20:23]
	v_mfma_f32_16x16x32_bf16 v[16:19], v[172:175], v[212:215], v[16:19]
	v_mfma_f32_16x16x32_bf16 v[12:15], v[146:149], v[220:223], v[12:15]
	v_mfma_f32_16x16x32_bf16 v[8:11], v[172:175], v[220:223], v[8:11]
	v_mfma_f32_16x16x32_bf16 v[4:7], v[146:149], v[228:231], v[4:7]
	v_mfma_f32_16x16x32_bf16 v[0:3], v[172:175], v[228:231], v[0:3]
	v_mfma_f32_16x16x32_bf16 v[28:31], v[168:171], v[208:211], v[28:31]
	v_mfma_f32_16x16x32_bf16 v[24:27], v[176:179], v[208:211], v[24:27]
	v_mfma_f32_16x16x32_bf16 v[20:23], v[168:171], v[216:219], v[20:23]
	v_mfma_f32_16x16x32_bf16 v[16:19], v[176:179], v[216:219], v[16:19]
	v_mfma_f32_16x16x32_bf16 v[12:15], v[168:171], v[224:227], v[12:15]
	v_mfma_f32_16x16x32_bf16 v[8:11], v[176:179], v[224:227], v[8:11]
	v_mfma_f32_16x16x32_bf16 v[4:7], v[168:171], v[232:235], v[4:7]
	v_mfma_f32_16x16x32_bf16 v[0:3], v[176:179], v[232:235], v[0:3]
	v_mfma_f32_16x16x32_bf16 v[92:95], v[180:183], v[204:207], v[92:95]
	v_mfma_f32_16x16x32_bf16 v[88:91], v[188:191], v[204:207], v[88:91]
	v_mfma_f32_16x16x32_bf16 v[84:87], v[180:183], v[212:215], v[84:87]
	v_mfma_f32_16x16x32_bf16 v[80:83], v[188:191], v[212:215], v[80:83]
	v_mfma_f32_16x16x32_bf16 v[76:79], v[180:183], v[220:223], v[76:79]
	v_mfma_f32_16x16x32_bf16 v[72:75], v[188:191], v[220:223], v[72:75]
	v_mfma_f32_16x16x32_bf16 v[68:71], v[180:183], v[228:231], v[68:71]
	v_mfma_f32_16x16x32_bf16 v[64:67], v[188:191], v[228:231], v[64:67]
	v_mfma_f32_16x16x32_bf16 v[92:95], v[184:187], v[208:211], v[92:95]
	v_mfma_f32_16x16x32_bf16 v[88:91], v[200:203], v[208:211], v[88:91]
	v_mfma_f32_16x16x32_bf16 v[84:87], v[184:187], v[216:219], v[84:87]
	v_mfma_f32_16x16x32_bf16 v[80:83], v[200:203], v[216:219], v[80:83]
	v_mfma_f32_16x16x32_bf16 v[76:79], v[184:187], v[224:227], v[76:79]
	v_mfma_f32_16x16x32_bf16 v[72:75], v[200:203], v[224:227], v[72:75]
	v_mfma_f32_16x16x32_bf16 v[68:71], v[184:187], v[232:235], v[68:71]
	v_mfma_f32_16x16x32_bf16 v[64:67], v[200:203], v[232:235], v[64:67]
	s_barrier
	s_add_i32 s82, s82, 2
	s_add_u32 s80, s80, 0x100
	s_addc_u32 s81, s81, 0
	s_add_u32 s36, s36, 0x100
	s_addc_u32 s37, s37, 0
	s_cmp_gt_u32 s82, 29
	s_cbranch_scc0 .LBB0_203
	s_and_b64 vcc, exec, s[48:49]
	s_cbranch_vccz .LBB0_206
	s_barrier

.LBB0_316:
	s_add_u32 s18, s12, 0x100
	s_addc_u32 s19, s13, 0
	s_add_i32 s83, 0, 0x10000
	s_cmp_eq_u32 s82, 4
	s_cselect_b32 s59, s61, s19
	s_cselect_b32 s58, s60, s18
	v_add_u32_e32 v96, s83, v174
	s_cselect_b32 s35, s55, s81
	s_cselect_b32 s34, s79, s80
	s_add_i32 s84, 0, 0x14000
	ds_read_b128 v[142:145], v96
	ds_read_b128 v[146:149], v96 offset:1024
	ds_read_b128 v[150:153], v96 offset:2048
	ds_read_b128 v[154:157], v96 offset:3072
	v_add_u32_e32 v96, s84, v174
	ds_read_b128 v[168:171], v96
	ds_read_b128 v[176:179], v96 offset:1024
	ds_read_b128 v[180:183], v96 offset:2048
	ds_read_b128 v[184:187], v96 offset:3072
	v_lshl_add_u64 v[192:193], s[12:13], 0, v[140:141]
	s_add_i32 m0, s70, 0xc000
	ds_read_b128 v[188:191], v175
	ds_read_b128 v[200:203], v175 offset:1024
	ds_read_b128 v[204:207], v175 offset:2048
	ds_read_b128 v[208:211], v175 offset:3072
	ds_read_b128 v[212:215], v175 offset:4096
	ds_read_b128 v[216:219], v175 offset:5120
	ds_read_b128 v[220:223], v175 offset:6144
	ds_read_b128 v[224:227], v175 offset:7168
	global_load_lds_dwordx4 v[192:193], off
	v_lshl_add_u64 v[192:193], s[12:13], 0, v[138:139]
	s_add_i32 m0, s70, 0xe000
	s_nop 0
	global_load_lds_dwordx4 v[192:193], off
	s_waitcnt vmcnt(8)
	s_waitcnt lgkmcnt(0)
	s_barrier
	s_waitcnt lgkmcnt(0)
	v_mfma_f32_16x16x32_bf16 v[126:129], v[142:145], v[188:191], v[126:129]
	v_mfma_f32_16x16x32_bf16 v[122:125], v[150:153], v[188:191], v[122:125]
	v_mfma_f32_16x16x32_bf16 v[110:113], v[142:145], v[204:207], v[110:113]
	v_mfma_f32_16x16x32_bf16 v[106:109], v[150:153], v[204:207], v[106:109]
	v_mfma_f32_16x16x32_bf16 v[92:95], v[142:145], v[212:215], v[92:95]
	v_mfma_f32_16x16x32_bf16 v[88:91], v[150:153], v[212:215], v[88:91]
	v_mfma_f32_16x16x32_bf16 v[76:79], v[142:145], v[220:223], v[76:79]
	v_mfma_f32_16x16x32_bf16 v[72:75], v[150:153], v[220:223], v[72:75]
	v_mfma_f32_16x16x32_bf16 v[126:129], v[146:149], v[200:203], v[126:129]
	v_mfma_f32_16x16x32_bf16 v[122:125], v[154:157], v[200:203], v[122:125]
	v_mfma_f32_16x16x32_bf16 v[110:113], v[146:149], v[208:211], v[110:113]
	v_mfma_f32_16x16x32_bf16 v[106:109], v[154:157], v[208:211], v[106:109]
	v_mfma_f32_16x16x32_bf16 v[92:95], v[146:149], v[216:219], v[92:95]
	v_mfma_f32_16x16x32_bf16 v[88:91], v[154:157], v[216:219], v[88:91]
	v_mfma_f32_16x16x32_bf16 v[76:79], v[146:149], v[224:227], v[76:79]
	v_mfma_f32_16x16x32_bf16 v[72:75], v[154:157], v[224:227], v[72:75]
	v_mfma_f32_16x16x32_bf16 v[118:121], v[168:171], v[188:191], v[118:121]
	v_mfma_f32_16x16x32_bf16 v[114:117], v[180:183], v[188:191], v[114:117]
	v_mfma_f32_16x16x32_bf16 v[102:105], v[168:171], v[204:207], v[102:105]
	v_mfma_f32_16x16x32_bf16 v[98:101], v[180:183], v[204:207], v[98:101]
	v_mfma_f32_16x16x32_bf16 v[84:87], v[168:171], v[212:215], v[84:87]
	v_mfma_f32_16x16x32_bf16 v[80:83], v[180:183], v[212:215], v[80:83]
	v_mfma_f32_16x16x32_bf16 v[68:71], v[168:171], v[220:223], v[68:71]
	v_mfma_f32_16x16x32_bf16 v[64:67], v[180:183], v[220:223], v[64:67]
	v_mfma_f32_16x16x32_bf16 v[118:121], v[176:179], v[200:203], v[118:121]
	v_mfma_f32_16x16x32_bf16 v[114:117], v[184:187], v[200:203], v[114:117]
	v_mfma_f32_16x16x32_bf16 v[102:105], v[176:179], v[208:211], v[102:105]
	v_mfma_f32_16x16x32_bf16 v[98:101], v[184:187], v[208:211], v[98:101]
	v_mfma_f32_16x16x32_bf16 v[84:87], v[176:179], v[216:219], v[84:87]
	v_mfma_f32_16x16x32_bf16 v[80:83], v[184:187], v[216:219], v[80:83]
	v_mfma_f32_16x16x32_bf16 v[68:71], v[176:179], v[224:227], v[68:71]
	v_mfma_f32_16x16x32_bf16 v[64:67], v[184:187], v[224:227], v[64:67]
	s_barrier
	s_add_i32 s12, s83, s69
	v_lshl_add_u64 v[192:193], s[34:35], 0, v[134:135]
	s_mov_b32 m0, s12
	ds_read_b128 v[188:191], v175 offset:16384
	ds_read_b128 v[200:203], v175 offset:17408
	ds_read_b128 v[204:207], v175 offset:18432
	ds_read_b128 v[208:211], v175 offset:19456
	ds_read_b128 v[212:215], v175 offset:20480
	ds_read_b128 v[216:219], v175 offset:21504
	ds_read_b128 v[220:223], v175 offset:22528
	ds_read_b128 v[224:227], v175 offset:23552
	global_load_lds_dwordx4 v[192:193], off
	s_add_i32 m0, s12, 0x2000
	s_add_u32 s12, s34, 0x20000
	v_lshl_add_u64 v[196:197], s[34:35], 0, v[130:131]
	s_addc_u32 s13, s35, 0
	s_add_i32 s83, s84, s69
	global_load_lds_dwordx4 v[196:197], off
	v_lshl_add_u64 v[198:199], s[12:13], 0, v[134:135]
	s_mov_b32 m0, s83
	v_lshl_add_u64 v[228:229], s[58:59], 0, v[132:133]
	global_load_lds_dwordx4 v[198:199], off
	v_lshl_add_u64 v[198:199], s[12:13], 0, v[130:131]
	s_add_i32 m0, s83, 0x2000
	s_nop 0
	global_load_lds_dwordx4 v[198:199], off
	v_lshl_add_u64 v[198:199], s[58:59], 0, v[136:137]
	s_mov_b32 m0, s70
	s_nop 0
	global_load_lds_dwordx4 v[198:199], off
	s_mov_b32 m0, s71
	s_nop 0
	global_load_lds_dwordx4 v[228:229], off
	s_waitcnt vmcnt(8)
	s_waitcnt lgkmcnt(0)
	s_barrier
	s_waitcnt lgkmcnt(0)
	v_mfma_f32_16x16x32_bf16 v[60:63], v[142:145], v[188:191], v[60:63]
	v_mfma_f32_16x16x32_bf16 v[56:59], v[150:153], v[188:191], v[56:59]
	v_mfma_f32_16x16x32_bf16 v[44:47], v[142:145], v[204:207], v[44:47]
	v_mfma_f32_16x16x32_bf16 v[40:43], v[150:153], v[204:207], v[40:43]
	v_mfma_f32_16x16x32_bf16 v[28:31], v[142:145], v[212:215], v[28:31]
	v_mfma_f32_16x16x32_bf16 v[24:27], v[150:153], v[212:215], v[24:27]
	v_mfma_f32_16x16x32_bf16 v[12:15], v[142:145], v[220:223], v[12:15]
	v_mfma_f32_16x16x32_bf16 v[8:11], v[150:153], v[220:223], v[8:11]
	v_mfma_f32_16x16x32_bf16 v[60:63], v[146:149], v[200:203], v[60:63]
	v_mfma_f32_16x16x32_bf16 v[56:59], v[154:157], v[200:203], v[56:59]
	v_mfma_f32_16x16x32_bf16 v[44:47], v[146:149], v[208:211], v[44:47]
	v_mfma_f32_16x16x32_bf16 v[40:43], v[154:157], v[208:211], v[40:43]
	v_mfma_f32_16x16x32_bf16 v[28:31], v[146:149], v[216:219], v[28:31]
	v_mfma_f32_16x16x32_bf16 v[24:27], v[154:157], v[216:219], v[24:27]
	v_mfma_f32_16x16x32_bf16 v[12:15], v[146:149], v[224:227], v[12:15]
	v_mfma_f32_16x16x32_bf16 v[8:11], v[154:157], v[224:227], v[8:11]
	v_mfma_f32_16x16x32_bf16 v[52:55], v[168:171], v[188:191], v[52:55]
	v_mfma_f32_16x16x32_bf16 v[48:51], v[180:183], v[188:191], v[48:51]
	v_mfma_f32_16x16x32_bf16 v[36:39], v[168:171], v[204:207], v[36:39]
	v_mfma_f32_16x16x32_bf16 v[32:35], v[180:183], v[204:207], v[32:35]
	v_mfma_f32_16x16x32_bf16 v[20:23], v[168:171], v[212:215], v[20:23]
	v_mfma_f32_16x16x32_bf16 v[16:19], v[180:183], v[212:215], v[16:19]
	v_mfma_f32_16x16x32_bf16 v[4:7], v[168:171], v[220:223], v[4:7]
	v_mfma_f32_16x16x32_bf16 v[0:3], v[180:183], v[220:223], v[0:3]
	v_mfma_f32_16x16x32_bf16 v[52:55], v[176:179], v[200:203], v[52:55]
	v_mfma_f32_16x16x32_bf16 v[48:51], v[184:187], v[200:203], v[48:51]
	v_mfma_f32_16x16x32_bf16 v[36:39], v[176:179], v[208:211], v[36:39]
	v_mfma_f32_16x16x32_bf16 v[32:35], v[184:187], v[208:211], v[32:35]
	v_mfma_f32_16x16x32_bf16 v[20:23], v[176:179], v[216:219], v[20:23]
	v_mfma_f32_16x16x32_bf16 v[16:19], v[184:187], v[216:219], v[16:19]
	v_mfma_f32_16x16x32_bf16 v[4:7], v[176:179], v[224:227], v[4:7]
	v_mfma_f32_16x16x32_bf16 v[0:3], v[184:187], v[224:227], v[0:3]
	s_barrier
	s_add_i32 s83, 0, 0x18000
	v_add_u32_e32 v96, s83, v174
	s_add_i32 s84, 0, 0x1c000
	ds_read_b128 v[142:145], v96
	ds_read_b128 v[146:149], v96 offset:1024
	ds_read_b128 v[150:153], v96 offset:2048
	ds_read_b128 v[154:157], v96 offset:3072
	v_add_u32_e32 v96, s84, v174
	ds_read_b128 v[168:171], v96
	ds_read_b128 v[176:179], v96 offset:1024
	ds_read_b128 v[180:183], v96 offset:2048
	ds_read_b128 v[184:187], v96 offset:3072
	s_add_u32 s12, s58, 0x330000
	s_addc_u32 s13, s59, 0
	s_mov_b32 m0, s26
	v_lshl_add_u64 v[230:231], s[12:13], 0, v[136:137]
	ds_read_b128 v[188:191], v175 offset:32768
	ds_read_b128 v[200:203], v175 offset:33792
	ds_read_b128 v[204:207], v175 offset:34816
	ds_read_b128 v[208:211], v175 offset:35840
	ds_read_b128 v[212:215], v175 offset:36864
	ds_read_b128 v[216:219], v175 offset:37888
	ds_read_b128 v[220:223], v175 offset:38912
	ds_read_b128 v[224:227], v175 offset:39936
	global_load_lds_dwordx4 v[230:231], off
	v_lshl_add_u64 v[230:231], s[12:13], 0, v[132:133]
	s_mov_b32 m0, s65
	s_nop 0
	global_load_lds_dwordx4 v[230:231], off
	s_waitcnt vmcnt(8)
	s_waitcnt lgkmcnt(0)
	s_barrier
	s_waitcnt lgkmcnt(0)
	v_mfma_f32_16x16x32_bf16 v[126:129], v[142:145], v[188:191], v[126:129]
	v_mfma_f32_16x16x32_bf16 v[122:125], v[150:153], v[188:191], v[122:125]
	v_mfma_f32_16x16x32_bf16 v[110:113], v[142:145], v[204:207], v[110:113]
	v_mfma_f32_16x16x32_bf16 v[106:109], v[150:153], v[204:207], v[106:109]
	v_mfma_f32_16x16x32_bf16 v[92:95], v[142:145], v[212:215], v[92:95]
	v_mfma_f32_16x16x32_bf16 v[88:91], v[150:153], v[212:215], v[88:91]
	v_mfma_f32_16x16x32_bf16 v[76:79], v[142:145], v[220:223], v[76:79]
	v_mfma_f32_16x16x32_bf16 v[72:75], v[150:153], v[220:223], v[72:75]
	v_mfma_f32_16x16x32_bf16 v[126:129], v[146:149], v[200:203], v[126:129]
	v_mfma_f32_16x16x32_bf16 v[122:125], v[154:157], v[200:203], v[122:125]
	v_mfma_f32_16x16x32_bf16 v[110:113], v[146:149], v[208:211], v[110:113]
	v_mfma_f32_16x16x32_bf16 v[106:109], v[154:157], v[208:211], v[106:109]
	v_mfma_f32_16x16x32_bf16 v[92:95], v[146:149], v[216:219], v[92:95]
	v_mfma_f32_16x16x32_bf16 v[88:91], v[154:157], v[216:219], v[88:91]
	v_mfma_f32_16x16x32_bf16 v[76:79], v[146:149], v[224:227], v[76:79]
	v_mfma_f32_16x16x32_bf16 v[72:75], v[154:157], v[224:227], v[72:75]
	v_mfma_f32_16x16x32_bf16 v[118:121], v[168:171], v[188:191], v[118:121]
	v_mfma_f32_16x16x32_bf16 v[114:117], v[180:183], v[188:191], v[114:117]
	v_mfma_f32_16x16x32_bf16 v[102:105], v[168:171], v[204:207], v[102:105]
	v_mfma_f32_16x16x32_bf16 v[98:101], v[180:183], v[204:207], v[98:101]
	v_mfma_f32_16x16x32_bf16 v[84:87], v[168:171], v[212:215], v[84:87]
	v_mfma_f32_16x16x32_bf16 v[80:83], v[180:183], v[212:215], v[80:83]
	v_mfma_f32_16x16x32_bf16 v[68:71], v[168:171], v[220:223], v[68:71]
	v_mfma_f32_16x16x32_bf16 v[64:67], v[180:183], v[220:223], v[64:67]
	v_mfma_f32_16x16x32_bf16 v[118:121], v[176:179], v[200:203], v[118:121]
	v_mfma_f32_16x16x32_bf16 v[114:117], v[184:187], v[200:203], v[114:117]
	v_mfma_f32_16x16x32_bf16 v[102:105], v[176:179], v[208:211], v[102:105]
	v_mfma_f32_16x16x32_bf16 v[98:101], v[184:187], v[208:211], v[98:101]
	v_mfma_f32_16x16x32_bf16 v[84:87], v[176:179], v[216:219], v[84:87]
	v_mfma_f32_16x16x32_bf16 v[80:83], v[184:187], v[216:219], v[80:83]
	v_mfma_f32_16x16x32_bf16 v[68:71], v[176:179], v[224:227], v[68:71]
	v_mfma_f32_16x16x32_bf16 v[64:67], v[184:187], v[224:227], v[64:67]
	s_barrier
	s_add_i32 s12, s83, s69
	v_lshl_add_u64 v[192:193], v[192:193], 0, s[30:31]
	s_mov_b32 m0, s12
	ds_read_b128 v[188:191], v175 offset:49152
	ds_read_b128 v[200:203], v175 offset:50176
	ds_read_b128 v[204:207], v175 offset:51200
	ds_read_b128 v[208:211], v175 offset:52224
	ds_read_b128 v[212:215], v175 offset:53248
	ds_read_b128 v[216:219], v175 offset:54272
	ds_read_b128 v[220:223], v175 offset:55296
	ds_read_b128 v[224:227], v175 offset:56320
	global_load_lds_dwordx4 v[192:193], off
	s_add_i32 m0, s12, 0x2000
	s_add_u32 s12, s34, 0x20080
	v_lshl_add_u64 v[192:193], v[196:197], 0, s[30:31]
	s_addc_u32 s13, s35, 0
	s_add_i32 s34, s84, s69
	global_load_lds_dwordx4 v[192:193], off
	v_lshl_add_u64 v[192:193], s[12:13], 0, v[134:135]
	s_mov_b32 m0, s34
	s_nop 0
	global_load_lds_dwordx4 v[192:193], off
	v_lshl_add_u64 v[192:193], s[12:13], 0, v[130:131]
	s_add_i32 m0, s34, 0x2000
	s_nop 0
	global_load_lds_dwordx4 v[192:193], off
	v_lshl_add_u64 v[192:193], v[198:199], 0, s[30:31]
	s_mov_b32 m0, s73
	s_nop 0
	global_load_lds_dwordx4 v[192:193], off
	v_lshl_add_u64 v[192:193], v[228:229], 0, s[30:31]
	s_mov_b32 m0, s74
	s_nop 0
	global_load_lds_dwordx4 v[192:193], off
	s_waitcnt vmcnt(8)
	s_waitcnt lgkmcnt(0)
	s_barrier
	s_waitcnt lgkmcnt(0)
	v_mfma_f32_16x16x32_bf16 v[60:63], v[142:145], v[188:191], v[60:63]
	v_mfma_f32_16x16x32_bf16 v[56:59], v[150:153], v[188:191], v[56:59]
	v_mfma_f32_16x16x32_bf16 v[44:47], v[142:145], v[204:207], v[44:47]
	v_mfma_f32_16x16x32_bf16 v[40:43], v[150:153], v[204:207], v[40:43]
	v_mfma_f32_16x16x32_bf16 v[28:31], v[142:145], v[212:215], v[28:31]
	v_mfma_f32_16x16x32_bf16 v[24:27], v[150:153], v[212:215], v[24:27]
	v_mfma_f32_16x16x32_bf16 v[12:15], v[142:145], v[220:223], v[12:15]
	v_mfma_f32_16x16x32_bf16 v[8:11], v[150:153], v[220:223], v[8:11]
	v_mfma_f32_16x16x32_bf16 v[60:63], v[146:149], v[200:203], v[60:63]
	v_mfma_f32_16x16x32_bf16 v[56:59], v[154:157], v[200:203], v[56:59]
	v_mfma_f32_16x16x32_bf16 v[44:47], v[146:149], v[208:211], v[44:47]
	v_mfma_f32_16x16x32_bf16 v[40:43], v[154:157], v[208:211], v[40:43]
	v_mfma_f32_16x16x32_bf16 v[28:31], v[146:149], v[216:219], v[28:31]
	v_mfma_f32_16x16x32_bf16 v[24:27], v[154:157], v[216:219], v[24:27]
	v_mfma_f32_16x16x32_bf16 v[12:15], v[146:149], v[224:227], v[12:15]
	v_mfma_f32_16x16x32_bf16 v[8:11], v[154:157], v[224:227], v[8:11]
	v_mfma_f32_16x16x32_bf16 v[52:55], v[168:171], v[188:191], v[52:55]
	v_mfma_f32_16x16x32_bf16 v[48:51], v[180:183], v[188:191], v[48:51]
	v_mfma_f32_16x16x32_bf16 v[36:39], v[168:171], v[204:207], v[36:39]
	v_mfma_f32_16x16x32_bf16 v[32:35], v[180:183], v[204:207], v[32:35]
	v_mfma_f32_16x16x32_bf16 v[20:23], v[168:171], v[212:215], v[20:23]
	v_mfma_f32_16x16x32_bf16 v[16:19], v[180:183], v[212:215], v[16:19]
	v_mfma_f32_16x16x32_bf16 v[4:7], v[168:171], v[220:223], v[4:7]
	v_mfma_f32_16x16x32_bf16 v[0:3], v[180:183], v[220:223], v[0:3]
	v_mfma_f32_16x16x32_bf16 v[52:55], v[176:179], v[200:203], v[52:55]
	v_mfma_f32_16x16x32_bf16 v[48:51], v[184:187], v[200:203], v[48:51]
	v_mfma_f32_16x16x32_bf16 v[36:39], v[176:179], v[208:211], v[36:39]
	v_mfma_f32_16x16x32_bf16 v[32:35], v[184:187], v[208:211], v[32:35]
	v_mfma_f32_16x16x32_bf16 v[20:23], v[176:179], v[216:219], v[20:23]
	v_mfma_f32_16x16x32_bf16 v[16:19], v[184:187], v[216:219], v[16:19]
	v_mfma_f32_16x16x32_bf16 v[4:7], v[176:179], v[224:227], v[4:7]
	v_mfma_f32_16x16x32_bf16 v[0:3], v[184:187], v[224:227], v[0:3]
	s_barrier
	s_add_i32 s82, s82, 2
	s_add_u32 s80, s80, 0x100
	s_addc_u32 s81, s81, 0
	s_cmp_gt_u32 s82, 5
	s_mov_b64 s[12:13], s[18:19]
	s_cbranch_scc0 .LBB0_316
	s_and_b64 vcc, exec, s[50:51]
	s_cbranch_vccz .LBB0_319
	s_barrier

.LBB0_398:
	s_add_u32 s18, s54, 0x100
	s_addc_u32 s19, s55, 0
	s_add_i32 s79, 0, 0x10000
	s_cmp_eq_u32 s78, 4
	s_cselect_b32 s59, s49, s19
	s_cselect_b32 s58, s48, s18
	v_add_u32_e32 v144, s79, v147
	s_cselect_b32 s35, s37, s77
	s_cselect_b32 s34, s75, s76
	s_add_i32 s80, 0, 0x14000
	ds_read_b128 v[140:143], v144
	ds_read_b128 v[150:153], v144 offset:1024
	ds_read_b128 v[154:157], v144 offset:2048
	ds_read_b128 v[168:171], v144 offset:3072
	v_add_u32_e32 v144, s80, v147
	ds_read_b128 v[172:175], v144
	ds_read_b128 v[176:179], v144 offset:1024
	ds_read_b128 v[180:183], v144 offset:2048
	ds_read_b128 v[184:187], v144 offset:3072
	v_lshl_add_u64 v[144:145], s[54:55], 0, v[138:139]
	s_add_i32 m0, s65, 0xc000
	ds_read_b128 v[188:191], v149
	ds_read_b128 v[200:203], v149 offset:1024
	ds_read_b128 v[204:207], v149 offset:2048
	ds_read_b128 v[208:211], v149 offset:3072
	ds_read_b128 v[212:215], v149 offset:4096
	ds_read_b128 v[216:219], v149 offset:5120
	ds_read_b128 v[220:223], v149 offset:6144
	ds_read_b128 v[224:227], v149 offset:7168
	global_load_lds_dwordx4 v[144:145], off
	v_lshl_add_u64 v[144:145], s[54:55], 0, v[136:137]
	s_add_i32 m0, s65, 0xe000
	s_nop 0
	global_load_lds_dwordx4 v[144:145], off
	s_waitcnt vmcnt(8)
	s_waitcnt lgkmcnt(0)
	s_barrier
	s_waitcnt lgkmcnt(0)
	v_mfma_f32_16x16x32_bf16 v[126:129], v[140:143], v[188:191], v[126:129]
	v_mfma_f32_16x16x32_bf16 v[122:125], v[154:157], v[188:191], v[122:125]
	v_mfma_f32_16x16x32_bf16 v[110:113], v[140:143], v[204:207], v[110:113]
	v_mfma_f32_16x16x32_bf16 v[106:109], v[154:157], v[204:207], v[106:109]
	v_mfma_f32_16x16x32_bf16 v[92:95], v[140:143], v[212:215], v[92:95]
	v_mfma_f32_16x16x32_bf16 v[88:91], v[154:157], v[212:215], v[88:91]
	v_mfma_f32_16x16x32_bf16 v[76:79], v[140:143], v[220:223], v[76:79]
	v_mfma_f32_16x16x32_bf16 v[72:75], v[154:157], v[220:223], v[72:75]
	v_mfma_f32_16x16x32_bf16 v[126:129], v[150:153], v[200:203], v[126:129]
	v_mfma_f32_16x16x32_bf16 v[122:125], v[168:171], v[200:203], v[122:125]
	v_mfma_f32_16x16x32_bf16 v[110:113], v[150:153], v[208:211], v[110:113]
	v_mfma_f32_16x16x32_bf16 v[106:109], v[168:171], v[208:211], v[106:109]
	v_mfma_f32_16x16x32_bf16 v[92:95], v[150:153], v[216:219], v[92:95]
	v_mfma_f32_16x16x32_bf16 v[88:91], v[168:171], v[216:219], v[88:91]
	v_mfma_f32_16x16x32_bf16 v[76:79], v[150:153], v[224:227], v[76:79]
	v_mfma_f32_16x16x32_bf16 v[72:75], v[168:171], v[224:227], v[72:75]
	v_mfma_f32_16x16x32_bf16 v[118:121], v[172:175], v[188:191], v[118:121]
	v_mfma_f32_16x16x32_bf16 v[114:117], v[180:183], v[188:191], v[114:117]
	v_mfma_f32_16x16x32_bf16 v[102:105], v[172:175], v[204:207], v[102:105]
	v_mfma_f32_16x16x32_bf16 v[98:101], v[180:183], v[204:207], v[98:101]
	v_mfma_f32_16x16x32_bf16 v[84:87], v[172:175], v[212:215], v[84:87]
	v_mfma_f32_16x16x32_bf16 v[80:83], v[180:183], v[212:215], v[80:83]
	v_mfma_f32_16x16x32_bf16 v[68:71], v[172:175], v[220:223], v[68:71]
	v_mfma_f32_16x16x32_bf16 v[64:67], v[180:183], v[220:223], v[64:67]
	v_mfma_f32_16x16x32_bf16 v[118:121], v[176:179], v[200:203], v[118:121]
	v_mfma_f32_16x16x32_bf16 v[114:117], v[184:187], v[200:203], v[114:117]
	v_mfma_f32_16x16x32_bf16 v[102:105], v[176:179], v[208:211], v[102:105]
	v_mfma_f32_16x16x32_bf16 v[98:101], v[184:187], v[208:211], v[98:101]
	v_mfma_f32_16x16x32_bf16 v[84:87], v[176:179], v[216:219], v[84:87]
	v_mfma_f32_16x16x32_bf16 v[80:83], v[184:187], v[216:219], v[80:83]
	v_mfma_f32_16x16x32_bf16 v[68:71], v[176:179], v[224:227], v[68:71]
	v_mfma_f32_16x16x32_bf16 v[64:67], v[184:187], v[224:227], v[64:67]
	s_barrier
	s_add_i32 s54, s79, s61
	v_lshl_add_u64 v[144:145], s[34:35], 0, v[96:97]
	s_mov_b32 m0, s54
	ds_read_b128 v[188:191], v149 offset:16384
	ds_read_b128 v[200:203], v149 offset:17408
	ds_read_b128 v[204:207], v149 offset:18432
	ds_read_b128 v[208:211], v149 offset:19456
	ds_read_b128 v[212:215], v149 offset:20480
	ds_read_b128 v[216:219], v149 offset:21504
	ds_read_b128 v[220:223], v149 offset:22528
	ds_read_b128 v[224:227], v149 offset:23552
	global_load_lds_dwordx4 v[144:145], off
	s_add_i32 m0, s54, 0x2000
	s_add_u32 s54, s34, 0x20000
	v_lshl_add_u64 v[192:193], s[34:35], 0, v[130:131]
	s_addc_u32 s55, s35, 0
	s_add_i32 s79, s80, s61
	global_load_lds_dwordx4 v[192:193], off
	v_lshl_add_u64 v[196:197], s[54:55], 0, v[96:97]
	s_mov_b32 m0, s79
	v_lshl_add_u64 v[198:199], s[58:59], 0, v[132:133]
	global_load_lds_dwordx4 v[196:197], off
	v_lshl_add_u64 v[196:197], s[54:55], 0, v[130:131]
	s_add_i32 m0, s79, 0x2000
	s_nop 0
	global_load_lds_dwordx4 v[196:197], off
	v_lshl_add_u64 v[196:197], s[58:59], 0, v[134:135]
	s_mov_b32 m0, s65
	s_nop 0
	global_load_lds_dwordx4 v[196:197], off
	s_mov_b32 m0, s66
	s_nop 0
	global_load_lds_dwordx4 v[198:199], off
	s_waitcnt vmcnt(8)
	s_waitcnt lgkmcnt(0)
	s_barrier
	s_waitcnt lgkmcnt(0)
	v_mfma_f32_16x16x32_bf16 v[60:63], v[140:143], v[188:191], v[60:63]
	v_mfma_f32_16x16x32_bf16 v[56:59], v[154:157], v[188:191], v[56:59]
	v_mfma_f32_16x16x32_bf16 v[44:47], v[140:143], v[204:207], v[44:47]
	v_mfma_f32_16x16x32_bf16 v[40:43], v[154:157], v[204:207], v[40:43]
	v_mfma_f32_16x16x32_bf16 v[28:31], v[140:143], v[212:215], v[28:31]
	v_mfma_f32_16x16x32_bf16 v[24:27], v[154:157], v[212:215], v[24:27]
	v_mfma_f32_16x16x32_bf16 v[12:15], v[140:143], v[220:223], v[12:15]
	v_mfma_f32_16x16x32_bf16 v[8:11], v[154:157], v[220:223], v[8:11]
	v_mfma_f32_16x16x32_bf16 v[60:63], v[150:153], v[200:203], v[60:63]
	v_mfma_f32_16x16x32_bf16 v[56:59], v[168:171], v[200:203], v[56:59]
	v_mfma_f32_16x16x32_bf16 v[44:47], v[150:153], v[208:211], v[44:47]
	v_mfma_f32_16x16x32_bf16 v[40:43], v[168:171], v[208:211], v[40:43]
	v_mfma_f32_16x16x32_bf16 v[28:31], v[150:153], v[216:219], v[28:31]
	v_mfma_f32_16x16x32_bf16 v[24:27], v[168:171], v[216:219], v[24:27]
	v_mfma_f32_16x16x32_bf16 v[12:15], v[150:153], v[224:227], v[12:15]
	v_mfma_f32_16x16x32_bf16 v[8:11], v[168:171], v[224:227], v[8:11]
	v_mfma_f32_16x16x32_bf16 v[52:55], v[172:175], v[188:191], v[52:55]
	v_mfma_f32_16x16x32_bf16 v[48:51], v[180:183], v[188:191], v[48:51]
	v_mfma_f32_16x16x32_bf16 v[36:39], v[172:175], v[204:207], v[36:39]
	v_mfma_f32_16x16x32_bf16 v[32:35], v[180:183], v[204:207], v[32:35]
	v_mfma_f32_16x16x32_bf16 v[20:23], v[172:175], v[212:215], v[20:23]
	v_mfma_f32_16x16x32_bf16 v[16:19], v[180:183], v[212:215], v[16:19]
	v_mfma_f32_16x16x32_bf16 v[4:7], v[172:175], v[220:223], v[4:7]
	v_mfma_f32_16x16x32_bf16 v[0:3], v[180:183], v[220:223], v[0:3]
	v_mfma_f32_16x16x32_bf16 v[52:55], v[176:179], v[200:203], v[52:55]
	v_mfma_f32_16x16x32_bf16 v[48:51], v[184:187], v[200:203], v[48:51]
	v_mfma_f32_16x16x32_bf16 v[36:39], v[176:179], v[208:211], v[36:39]
	v_mfma_f32_16x16x32_bf16 v[32:35], v[184:187], v[208:211], v[32:35]
	v_mfma_f32_16x16x32_bf16 v[20:23], v[176:179], v[216:219], v[20:23]
	v_mfma_f32_16x16x32_bf16 v[16:19], v[184:187], v[216:219], v[16:19]
	v_mfma_f32_16x16x32_bf16 v[4:7], v[176:179], v[224:227], v[4:7]
	v_mfma_f32_16x16x32_bf16 v[0:3], v[184:187], v[224:227], v[0:3]
	s_barrier
	s_add_i32 s79, 0, 0x18000
	s_add_i32 s80, 0, 0x1c000
	v_add_u32_e32 v168, s79, v147
	v_add_u32_e32 v184, s80, v147
	ds_read_b128 v[140:143], v168
	ds_read_b128 v[150:153], v168 offset:1024
	ds_read_b128 v[154:157], v168 offset:2048
	ds_read_b128 v[168:171], v168 offset:3072
	ds_read_b128 v[172:175], v184
	ds_read_b128 v[176:179], v184 offset:1024
	ds_read_b128 v[180:183], v184 offset:2048
	ds_read_b128 v[184:187], v184 offset:3072
	s_add_u32 s54, s58, 0x330000
	s_addc_u32 s55, s59, 0
	s_mov_b32 m0, s67
	v_lshl_add_u64 v[228:229], s[54:55], 0, v[134:135]
	ds_read_b128 v[188:191], v149 offset:32768
	ds_read_b128 v[200:203], v149 offset:33792
	ds_read_b128 v[204:207], v149 offset:34816
	ds_read_b128 v[208:211], v149 offset:35840
	ds_read_b128 v[212:215], v149 offset:36864
	ds_read_b128 v[216:219], v149 offset:37888
	ds_read_b128 v[220:223], v149 offset:38912
	ds_read_b128 v[224:227], v149 offset:39936
	global_load_lds_dwordx4 v[228:229], off
	v_lshl_add_u64 v[228:229], s[54:55], 0, v[132:133]
	s_mov_b32 m0, s68
	s_nop 0
	global_load_lds_dwordx4 v[228:229], off
	s_waitcnt vmcnt(8)
	s_waitcnt lgkmcnt(0)
	s_barrier
	s_waitcnt lgkmcnt(0)
	v_mfma_f32_16x16x32_bf16 v[126:129], v[140:143], v[188:191], v[126:129]
	v_mfma_f32_16x16x32_bf16 v[122:125], v[154:157], v[188:191], v[122:125]
	v_mfma_f32_16x16x32_bf16 v[110:113], v[140:143], v[204:207], v[110:113]
	v_mfma_f32_16x16x32_bf16 v[106:109], v[154:157], v[204:207], v[106:109]
	v_mfma_f32_16x16x32_bf16 v[92:95], v[140:143], v[212:215], v[92:95]
	v_mfma_f32_16x16x32_bf16 v[88:91], v[154:157], v[212:215], v[88:91]
	v_mfma_f32_16x16x32_bf16 v[76:79], v[140:143], v[220:223], v[76:79]
	v_mfma_f32_16x16x32_bf16 v[72:75], v[154:157], v[220:223], v[72:75]
	v_mfma_f32_16x16x32_bf16 v[126:129], v[150:153], v[200:203], v[126:129]
	v_mfma_f32_16x16x32_bf16 v[122:125], v[168:171], v[200:203], v[122:125]
	v_mfma_f32_16x16x32_bf16 v[110:113], v[150:153], v[208:211], v[110:113]
	v_mfma_f32_16x16x32_bf16 v[106:109], v[168:171], v[208:211], v[106:109]
	v_mfma_f32_16x16x32_bf16 v[92:95], v[150:153], v[216:219], v[92:95]
	v_mfma_f32_16x16x32_bf16 v[88:91], v[168:171], v[216:219], v[88:91]
	v_mfma_f32_16x16x32_bf16 v[76:79], v[150:153], v[224:227], v[76:79]
	v_mfma_f32_16x16x32_bf16 v[72:75], v[168:171], v[224:227], v[72:75]
	v_mfma_f32_16x16x32_bf16 v[118:121], v[172:175], v[188:191], v[118:121]
	v_mfma_f32_16x16x32_bf16 v[114:117], v[180:183], v[188:191], v[114:117]
	v_mfma_f32_16x16x32_bf16 v[102:105], v[172:175], v[204:207], v[102:105]
	v_mfma_f32_16x16x32_bf16 v[98:101], v[180:183], v[204:207], v[98:101]
	v_mfma_f32_16x16x32_bf16 v[84:87], v[172:175], v[212:215], v[84:87]
	v_mfma_f32_16x16x32_bf16 v[80:83], v[180:183], v[212:215], v[80:83]
	v_mfma_f32_16x16x32_bf16 v[68:71], v[172:175], v[220:223], v[68:71]
	v_mfma_f32_16x16x32_bf16 v[64:67], v[180:183], v[220:223], v[64:67]
	v_mfma_f32_16x16x32_bf16 v[118:121], v[176:179], v[200:203], v[118:121]
	v_mfma_f32_16x16x32_bf16 v[114:117], v[184:187], v[200:203], v[114:117]
	v_mfma_f32_16x16x32_bf16 v[102:105], v[176:179], v[208:211], v[102:105]
	v_mfma_f32_16x16x32_bf16 v[98:101], v[184:187], v[208:211], v[98:101]
	v_mfma_f32_16x16x32_bf16 v[84:87], v[176:179], v[216:219], v[84:87]
	v_mfma_f32_16x16x32_bf16 v[80:83], v[184:187], v[216:219], v[80:83]
	v_mfma_f32_16x16x32_bf16 v[68:71], v[176:179], v[224:227], v[68:71]
	v_mfma_f32_16x16x32_bf16 v[64:67], v[184:187], v[224:227], v[64:67]
	s_barrier
	s_add_i32 s54, s79, s61
	v_lshl_add_u64 v[144:145], v[144:145], 0, s[30:31]
	s_mov_b32 m0, s54
	ds_read_b128 v[188:191], v149 offset:49152
	ds_read_b128 v[200:203], v149 offset:50176
	ds_read_b128 v[204:207], v149 offset:51200
	ds_read_b128 v[208:211], v149 offset:52224
	ds_read_b128 v[212:215], v149 offset:53248
	ds_read_b128 v[216:219], v149 offset:54272
	ds_read_b128 v[220:223], v149 offset:55296
	ds_read_b128 v[224:227], v149 offset:56320
	global_load_lds_dwordx4 v[144:145], off
	s_add_i32 m0, s54, 0x2000
	s_add_u32 s34, s34, 0x20080
	v_lshl_add_u64 v[144:145], v[192:193], 0, s[30:31]
	s_addc_u32 s35, s35, 0
	s_add_i32 s54, s80, s61
	global_load_lds_dwordx4 v[144:145], off
	v_lshl_add_u64 v[144:145], s[34:35], 0, v[96:97]
	s_mov_b32 m0, s54
	s_nop 0
	global_load_lds_dwordx4 v[144:145], off
	v_lshl_add_u64 v[144:145], s[34:35], 0, v[130:131]
	s_add_i32 m0, s54, 0x2000
	s_nop 0
	global_load_lds_dwordx4 v[144:145], off
	v_lshl_add_u64 v[144:145], v[196:197], 0, s[30:31]
	s_mov_b32 m0, s69
	s_nop 0
	global_load_lds_dwordx4 v[144:145], off
	v_lshl_add_u64 v[144:145], v[198:199], 0, s[30:31]
	s_mov_b32 m0, s70
	s_nop 0
	global_load_lds_dwordx4 v[144:145], off
	s_waitcnt vmcnt(8)
	s_waitcnt lgkmcnt(0)
	s_barrier
	s_waitcnt lgkmcnt(0)
	v_mfma_f32_16x16x32_bf16 v[60:63], v[140:143], v[188:191], v[60:63]
	v_mfma_f32_16x16x32_bf16 v[56:59], v[154:157], v[188:191], v[56:59]
	v_mfma_f32_16x16x32_bf16 v[44:47], v[140:143], v[204:207], v[44:47]
	v_mfma_f32_16x16x32_bf16 v[40:43], v[154:157], v[204:207], v[40:43]
	v_mfma_f32_16x16x32_bf16 v[28:31], v[140:143], v[212:215], v[28:31]
	v_mfma_f32_16x16x32_bf16 v[24:27], v[154:157], v[212:215], v[24:27]
	v_mfma_f32_16x16x32_bf16 v[12:15], v[140:143], v[220:223], v[12:15]
	v_mfma_f32_16x16x32_bf16 v[8:11], v[154:157], v[220:223], v[8:11]
	v_mfma_f32_16x16x32_bf16 v[60:63], v[150:153], v[200:203], v[60:63]
	v_mfma_f32_16x16x32_bf16 v[56:59], v[168:171], v[200:203], v[56:59]
	v_mfma_f32_16x16x32_bf16 v[44:47], v[150:153], v[208:211], v[44:47]
	v_mfma_f32_16x16x32_bf16 v[40:43], v[168:171], v[208:211], v[40:43]
	v_mfma_f32_16x16x32_bf16 v[28:31], v[150:153], v[216:219], v[28:31]
	v_mfma_f32_16x16x32_bf16 v[24:27], v[168:171], v[216:219], v[24:27]
	v_mfma_f32_16x16x32_bf16 v[12:15], v[150:153], v[224:227], v[12:15]
	v_mfma_f32_16x16x32_bf16 v[8:11], v[168:171], v[224:227], v[8:11]
	v_mfma_f32_16x16x32_bf16 v[52:55], v[172:175], v[188:191], v[52:55]
	v_mfma_f32_16x16x32_bf16 v[48:51], v[180:183], v[188:191], v[48:51]
	v_mfma_f32_16x16x32_bf16 v[36:39], v[172:175], v[204:207], v[36:39]
	v_mfma_f32_16x16x32_bf16 v[32:35], v[180:183], v[204:207], v[32:35]
	v_mfma_f32_16x16x32_bf16 v[20:23], v[172:175], v[212:215], v[20:23]
	v_mfma_f32_16x16x32_bf16 v[16:19], v[180:183], v[212:215], v[16:19]
	v_mfma_f32_16x16x32_bf16 v[4:7], v[172:175], v[220:223], v[4:7]
	v_mfma_f32_16x16x32_bf16 v[0:3], v[180:183], v[220:223], v[0:3]
	v_mfma_f32_16x16x32_bf16 v[52:55], v[176:179], v[200:203], v[52:55]
	v_mfma_f32_16x16x32_bf16 v[48:51], v[184:187], v[200:203], v[48:51]
	v_mfma_f32_16x16x32_bf16 v[36:39], v[176:179], v[208:211], v[36:39]
	v_mfma_f32_16x16x32_bf16 v[32:35], v[184:187], v[208:211], v[32:35]
	v_mfma_f32_16x16x32_bf16 v[20:23], v[176:179], v[216:219], v[20:23]
	v_mfma_f32_16x16x32_bf16 v[16:19], v[184:187], v[216:219], v[16:19]
	v_mfma_f32_16x16x32_bf16 v[4:7], v[176:179], v[224:227], v[4:7]
	v_mfma_f32_16x16x32_bf16 v[0:3], v[184:187], v[224:227], v[0:3]
	s_barrier
	s_add_i32 s78, s78, 2
	s_add_u32 s76, s76, 0x100
	s_addc_u32 s77, s77, 0
	s_cmp_gt_u32 s78, 5
	s_mov_b64 s[54:55], s[18:19]
	s_cbranch_scc0 .LBB0_398
	s_and_b64 vcc, exec, s[24:25]
	s_cbranch_vccz .LBB0_401
	s_barrier

.LBB0_962:
	s_add_i32 s12, s22, 1
	s_ashr_i32 s13, s12, 31
	s_mov_b32 s18, s22
	s_add_i32 s75, 0, 0x10000
	s_add_i32 s22, s22, 2
	s_lshl_b64 s[76:77], s[12:13], 7
	s_cmp_eq_u32 s18, 46
	v_add_u32_e32 v96, s75, v191
	s_cselect_b32 s19, s15, s74
	s_cselect_b32 s18, s14, s73
	s_cselect_b32 s13, s61, s72
	s_cselect_b32 s12, s60, s23
	s_add_i32 s78, 0, 0x14000
	ds_read_b128 v[132:135], v96
	ds_read_b128 v[136:139], v96 offset:1024
	ds_read_b128 v[180:183], v96 offset:2048
	ds_read_b128 v[184:187], v96 offset:3072
	v_add_u32_e32 v96, s78, v191
	ds_read_b128 v[196:199], v96
	ds_read_b128 v[200:203], v96 offset:1024
	ds_read_b128 v[204:207], v96 offset:2048
	ds_read_b128 v[208:211], v96 offset:3072
	s_add_u32 s76, s0, s76
	s_addc_u32 s77, s1, s77
	s_add_u32 s76, s76, 0xc0000
	s_addc_u32 s77, s77, 0
	v_lshl_add_u64 v[98:99], s[76:77], 0, v[146:147]
	s_add_i32 m0, s65, 0xc000
	ds_read_b128 v[212:215], v193
	ds_read_b128 v[216:219], v193 offset:1024
	ds_read_b128 v[220:223], v193 offset:2048
	ds_read_b128 v[224:227], v193 offset:3072
	ds_read_b128 v[228:231], v193 offset:4096
	ds_read_b128 v[232:235], v193 offset:5120
	ds_read_b128 v[236:239], v193 offset:6144
	ds_read_b128 v[240:243], v193 offset:7168
	global_load_lds_dwordx4 v[98:99], off
	v_lshl_add_u64 v[98:99], s[76:77], 0, v[142:143]
	s_add_i32 m0, s65, 0xe000
	s_nop 0
	global_load_lds_dwordx4 v[98:99], off
	s_waitcnt vmcnt(8)
	s_waitcnt lgkmcnt(0)
	s_barrier
	s_waitcnt lgkmcnt(0)
	v_mfma_f32_16x16x32_bf16 v[128:131], v[132:135], v[212:215], v[128:131]
	v_mfma_f32_16x16x32_bf16 v[124:127], v[180:183], v[212:215], v[124:127]
	v_mfma_f32_16x16x32_bf16 v[112:115], v[132:135], v[220:223], v[112:115]
	v_mfma_f32_16x16x32_bf16 v[108:111], v[180:183], v[220:223], v[108:111]
	v_mfma_f32_16x16x32_bf16 v[92:95], v[132:135], v[228:231], v[92:95]
	v_mfma_f32_16x16x32_bf16 v[88:91], v[180:183], v[228:231], v[88:91]
	v_mfma_f32_16x16x32_bf16 v[76:79], v[132:135], v[236:239], v[76:79]
	v_mfma_f32_16x16x32_bf16 v[72:75], v[180:183], v[236:239], v[72:75]
	v_mfma_f32_16x16x32_bf16 v[128:131], v[136:139], v[216:219], v[128:131]
	v_mfma_f32_16x16x32_bf16 v[124:127], v[184:187], v[216:219], v[124:127]
	v_mfma_f32_16x16x32_bf16 v[112:115], v[136:139], v[224:227], v[112:115]
	v_mfma_f32_16x16x32_bf16 v[108:111], v[184:187], v[224:227], v[108:111]
	v_mfma_f32_16x16x32_bf16 v[92:95], v[136:139], v[232:235], v[92:95]
	v_mfma_f32_16x16x32_bf16 v[88:91], v[184:187], v[232:235], v[88:91]
	v_mfma_f32_16x16x32_bf16 v[76:79], v[136:139], v[240:243], v[76:79]
	v_mfma_f32_16x16x32_bf16 v[72:75], v[184:187], v[240:243], v[72:75]
	v_mfma_f32_16x16x32_bf16 v[120:123], v[196:199], v[212:215], v[120:123]
	v_mfma_f32_16x16x32_bf16 v[116:119], v[204:207], v[212:215], v[116:119]
	v_mfma_f32_16x16x32_bf16 v[104:107], v[196:199], v[220:223], v[104:107]
	v_mfma_f32_16x16x32_bf16 v[98:101], v[204:207], v[220:223], v[100:103]
	v_mfma_f32_16x16x32_bf16 v[84:87], v[196:199], v[228:231], v[84:87]
	v_mfma_f32_16x16x32_bf16 v[80:83], v[204:207], v[228:231], v[80:83]
	v_mfma_f32_16x16x32_bf16 v[68:71], v[196:199], v[236:239], v[68:71]
	v_mfma_f32_16x16x32_bf16 v[64:67], v[204:207], v[236:239], v[64:67]
	v_mfma_f32_16x16x32_bf16 v[120:123], v[200:203], v[216:219], v[120:123]
	v_mfma_f32_16x16x32_bf16 v[116:119], v[208:211], v[216:219], v[116:119]
	v_mfma_f32_16x16x32_bf16 v[104:107], v[200:203], v[224:227], v[104:107]
	v_mfma_f32_16x16x32_bf16 v[98:101], v[208:211], v[224:227], v[98:101]
	v_mfma_f32_16x16x32_bf16 v[84:87], v[200:203], v[232:235], v[84:87]
	v_mfma_f32_16x16x32_bf16 v[80:83], v[208:211], v[232:235], v[80:83]
	v_mfma_f32_16x16x32_bf16 v[68:71], v[200:203], v[240:243], v[68:71]
	v_mfma_f32_16x16x32_bf16 v[64:67], v[208:211], v[240:243], v[64:67]
	s_barrier
	s_add_i32 s75, s75, s59
	v_lshl_add_u64 v[188:189], s[12:13], 0, v[144:145]
	s_mov_b32 m0, s75
	ds_read_b128 v[212:215], v193 offset:16384
	ds_read_b128 v[216:219], v193 offset:17408
	ds_read_b128 v[220:223], v193 offset:18432
	ds_read_b128 v[224:227], v193 offset:19456
	ds_read_b128 v[228:231], v193 offset:20480
	ds_read_b128 v[232:235], v193 offset:21504
	ds_read_b128 v[236:239], v193 offset:22528
	ds_read_b128 v[240:243], v193 offset:23552
	global_load_lds_dwordx4 v[188:189], off
	s_add_i32 m0, s75, 0x2000
	s_add_u32 s76, s12, 0xc0000
	v_lshl_add_u64 v[244:245], s[12:13], 0, v[140:141]
	s_addc_u32 s77, s13, 0
	s_add_i32 s75, s78, s59
	global_load_lds_dwordx4 v[244:245], off
	v_lshl_add_u64 v[102:103], s[76:77], 0, v[144:145]
	s_mov_b32 m0, s75
	v_lshl_add_u64 v[246:247], s[18:19], 0, v[146:147]
	global_load_lds_dwordx4 v[102:103], off
	v_lshl_add_u64 v[102:103], s[76:77], 0, v[140:141]
	s_add_i32 m0, s75, 0x2000
	v_lshl_add_u64 v[248:249], s[18:19], 0, v[142:143]
	global_load_lds_dwordx4 v[102:103], off
	s_mov_b32 m0, s65
	s_nop 0
	global_load_lds_dwordx4 v[246:247], off
	s_mov_b32 m0, s56
	s_nop 0
	global_load_lds_dwordx4 v[248:249], off
	s_waitcnt vmcnt(8)
	s_waitcnt lgkmcnt(0)
	s_barrier
	s_waitcnt lgkmcnt(0)
	v_mfma_f32_16x16x32_bf16 v[60:63], v[132:135], v[212:215], v[60:63]
	v_mfma_f32_16x16x32_bf16 v[56:59], v[180:183], v[212:215], v[56:59]
	v_mfma_f32_16x16x32_bf16 v[44:47], v[132:135], v[220:223], v[44:47]
	v_mfma_f32_16x16x32_bf16 v[40:43], v[180:183], v[220:223], v[40:43]
	v_mfma_f32_16x16x32_bf16 v[28:31], v[132:135], v[228:231], v[28:31]
	v_mfma_f32_16x16x32_bf16 v[24:27], v[180:183], v[228:231], v[24:27]
	v_mfma_f32_16x16x32_bf16 v[12:15], v[132:135], v[236:239], v[12:15]
	v_mfma_f32_16x16x32_bf16 v[8:11], v[180:183], v[236:239], v[8:11]
	v_mfma_f32_16x16x32_bf16 v[60:63], v[136:139], v[216:219], v[60:63]
	v_mfma_f32_16x16x32_bf16 v[56:59], v[184:187], v[216:219], v[56:59]
	v_mfma_f32_16x16x32_bf16 v[44:47], v[136:139], v[224:227], v[44:47]
	v_mfma_f32_16x16x32_bf16 v[40:43], v[184:187], v[224:227], v[40:43]
	v_mfma_f32_16x16x32_bf16 v[28:31], v[136:139], v[232:235], v[28:31]
	v_mfma_f32_16x16x32_bf16 v[24:27], v[184:187], v[232:235], v[24:27]
	v_mfma_f32_16x16x32_bf16 v[12:15], v[136:139], v[240:243], v[12:15]
	v_mfma_f32_16x16x32_bf16 v[8:11], v[184:187], v[240:243], v[8:11]
	v_mfma_f32_16x16x32_bf16 v[52:55], v[196:199], v[212:215], v[52:55]
	v_mfma_f32_16x16x32_bf16 v[48:51], v[204:207], v[212:215], v[48:51]
	v_mfma_f32_16x16x32_bf16 v[36:39], v[196:199], v[220:223], v[36:39]
	v_mfma_f32_16x16x32_bf16 v[32:35], v[204:207], v[220:223], v[32:35]
	v_mfma_f32_16x16x32_bf16 v[20:23], v[196:199], v[228:231], v[20:23]
	v_mfma_f32_16x16x32_bf16 v[16:19], v[204:207], v[228:231], v[16:19]
	v_mfma_f32_16x16x32_bf16 v[4:7], v[196:199], v[236:239], v[4:7]
	v_mfma_f32_16x16x32_bf16 v[0:3], v[204:207], v[236:239], v[0:3]
	v_mfma_f32_16x16x32_bf16 v[52:55], v[200:203], v[216:219], v[52:55]
	v_mfma_f32_16x16x32_bf16 v[48:51], v[208:211], v[216:219], v[48:51]
	v_mfma_f32_16x16x32_bf16 v[36:39], v[200:203], v[224:227], v[36:39]
	v_mfma_f32_16x16x32_bf16 v[32:35], v[208:211], v[224:227], v[32:35]
	v_mfma_f32_16x16x32_bf16 v[20:23], v[200:203], v[232:235], v[20:23]
	v_mfma_f32_16x16x32_bf16 v[16:19], v[208:211], v[232:235], v[16:19]
	v_mfma_f32_16x16x32_bf16 v[4:7], v[200:203], v[240:243], v[4:7]
	v_mfma_f32_16x16x32_bf16 v[0:3], v[208:211], v[240:243], v[0:3]
	s_barrier
	s_add_i32 s75, 0, 0x18000
	v_add_u32_e32 v96, s75, v191
	s_add_i32 s76, 0, 0x1c000
	ds_read_b128 v[132:135], v96
	ds_read_b128 v[136:139], v96 offset:1024
	ds_read_b128 v[180:183], v96 offset:2048
	ds_read_b128 v[184:187], v96 offset:3072
	v_add_u32_e32 v96, s76, v191
	ds_read_b128 v[196:199], v96
	ds_read_b128 v[200:203], v96 offset:1024
	ds_read_b128 v[204:207], v96 offset:2048
	ds_read_b128 v[208:211], v96 offset:3072
	s_add_u32 s18, s18, 0xc0000
	s_addc_u32 s19, s19, 0
	s_mov_b32 m0, s54
	v_lshl_add_u64 v[102:103], s[18:19], 0, v[146:147]
	ds_read_b128 v[212:215], v193 offset:32768
	ds_read_b128 v[216:219], v193 offset:33792
	ds_read_b128 v[220:223], v193 offset:34816
	ds_read_b128 v[224:227], v193 offset:35840
	ds_read_b128 v[228:231], v193 offset:36864
	ds_read_b128 v[232:235], v193 offset:37888
	ds_read_b128 v[236:239], v193 offset:38912
	ds_read_b128 v[240:243], v193 offset:39936
	global_load_lds_dwordx4 v[102:103], off
	v_lshl_add_u64 v[102:103], s[18:19], 0, v[142:143]
	s_mov_b32 m0, s55
	s_nop 0
	global_load_lds_dwordx4 v[102:103], off
	s_waitcnt vmcnt(8)
	s_waitcnt lgkmcnt(0)
	s_barrier
	s_waitcnt lgkmcnt(0)
	v_mfma_f32_16x16x32_bf16 v[128:131], v[132:135], v[212:215], v[128:131]
	v_mfma_f32_16x16x32_bf16 v[124:127], v[180:183], v[212:215], v[124:127]
	v_mfma_f32_16x16x32_bf16 v[112:115], v[132:135], v[220:223], v[112:115]
	v_mfma_f32_16x16x32_bf16 v[108:111], v[180:183], v[220:223], v[108:111]
	v_mfma_f32_16x16x32_bf16 v[92:95], v[132:135], v[228:231], v[92:95]
	v_mfma_f32_16x16x32_bf16 v[88:91], v[180:183], v[228:231], v[88:91]
	v_mfma_f32_16x16x32_bf16 v[76:79], v[132:135], v[236:239], v[76:79]
	v_mfma_f32_16x16x32_bf16 v[72:75], v[180:183], v[236:239], v[72:75]
	v_mfma_f32_16x16x32_bf16 v[128:131], v[136:139], v[216:219], v[128:131]
	v_mfma_f32_16x16x32_bf16 v[124:127], v[184:187], v[216:219], v[124:127]
	v_mfma_f32_16x16x32_bf16 v[112:115], v[136:139], v[224:227], v[112:115]
	v_mfma_f32_16x16x32_bf16 v[108:111], v[184:187], v[224:227], v[108:111]
	v_mfma_f32_16x16x32_bf16 v[92:95], v[136:139], v[232:235], v[92:95]
	v_mfma_f32_16x16x32_bf16 v[88:91], v[184:187], v[232:235], v[88:91]
	v_mfma_f32_16x16x32_bf16 v[76:79], v[136:139], v[240:243], v[76:79]
	v_mfma_f32_16x16x32_bf16 v[72:75], v[184:187], v[240:243], v[72:75]
	v_mfma_f32_16x16x32_bf16 v[120:123], v[196:199], v[212:215], v[120:123]
	v_mfma_f32_16x16x32_bf16 v[116:119], v[204:207], v[212:215], v[116:119]
	v_mfma_f32_16x16x32_bf16 v[102:105], v[196:199], v[220:223], v[104:107]
	v_mfma_f32_16x16x32_bf16 v[98:101], v[204:207], v[220:223], v[98:101]
	v_mfma_f32_16x16x32_bf16 v[84:87], v[196:199], v[228:231], v[84:87]
	v_mfma_f32_16x16x32_bf16 v[80:83], v[204:207], v[228:231], v[80:83]
	v_mfma_f32_16x16x32_bf16 v[68:71], v[196:199], v[236:239], v[68:71]
	v_mfma_f32_16x16x32_bf16 v[64:67], v[204:207], v[236:239], v[64:67]
	v_mfma_f32_16x16x32_bf16 v[120:123], v[200:203], v[216:219], v[120:123]
	v_mfma_f32_16x16x32_bf16 v[116:119], v[208:211], v[216:219], v[116:119]
	v_mfma_f32_16x16x32_bf16 v[104:107], v[200:203], v[224:227], v[102:105]
	v_mfma_f32_16x16x32_bf16 v[100:103], v[208:211], v[224:227], v[98:101]
	v_mfma_f32_16x16x32_bf16 v[84:87], v[200:203], v[232:235], v[84:87]
	v_mfma_f32_16x16x32_bf16 v[80:83], v[208:211], v[232:235], v[80:83]
	v_mfma_f32_16x16x32_bf16 v[68:71], v[200:203], v[240:243], v[68:71]
	v_mfma_f32_16x16x32_bf16 v[64:67], v[208:211], v[240:243], v[64:67]
	s_barrier
	s_add_i32 s18, s75, s59
	v_lshl_add_u64 v[98:99], v[188:189], 0, s[30:31]
	s_mov_b32 m0, s18
	ds_read_b128 v[212:215], v193 offset:49152
	ds_read_b128 v[216:219], v193 offset:50176
	ds_read_b128 v[220:223], v193 offset:51200
	ds_read_b128 v[224:227], v193 offset:52224
	ds_read_b128 v[228:231], v193 offset:53248
	ds_read_b128 v[232:235], v193 offset:54272
	ds_read_b128 v[236:239], v193 offset:55296
	ds_read_b128 v[240:243], v193 offset:56320
	global_load_lds_dwordx4 v[98:99], off
	s_add_i32 m0, s18, 0x2000
	s_add_u32 s12, s12, 0xc0080
	v_lshl_add_u64 v[98:99], v[244:245], 0, s[30:31]
	s_addc_u32 s13, s13, 0
	s_add_i32 s18, s76, s59
	global_load_lds_dwordx4 v[98:99], off
	v_lshl_add_u64 v[98:99], s[12:13], 0, v[144:145]
	s_mov_b32 m0, s18
	s_nop 0
	global_load_lds_dwordx4 v[98:99], off
	v_lshl_add_u64 v[98:99], s[12:13], 0, v[140:141]
	s_add_i32 m0, s18, 0x2000
	s_nop 0
	global_load_lds_dwordx4 v[98:99], off
	v_lshl_add_u64 v[98:99], v[246:247], 0, s[30:31]
	s_mov_b32 m0, s24
	s_nop 0
	global_load_lds_dwordx4 v[98:99], off
	v_lshl_add_u64 v[98:99], v[248:249], 0, s[30:31]
	s_mov_b32 m0, s25
	s_nop 0
	global_load_lds_dwordx4 v[98:99], off
	s_waitcnt vmcnt(8)
	s_waitcnt lgkmcnt(0)
	s_barrier
	s_waitcnt lgkmcnt(0)
	v_mfma_f32_16x16x32_bf16 v[60:63], v[132:135], v[212:215], v[60:63]
	v_mfma_f32_16x16x32_bf16 v[56:59], v[180:183], v[212:215], v[56:59]
	v_mfma_f32_16x16x32_bf16 v[44:47], v[132:135], v[220:223], v[44:47]
	v_mfma_f32_16x16x32_bf16 v[40:43], v[180:183], v[220:223], v[40:43]
	v_mfma_f32_16x16x32_bf16 v[28:31], v[132:135], v[228:231], v[28:31]
	v_mfma_f32_16x16x32_bf16 v[24:27], v[180:183], v[228:231], v[24:27]
	v_mfma_f32_16x16x32_bf16 v[12:15], v[132:135], v[236:239], v[12:15]
	v_mfma_f32_16x16x32_bf16 v[8:11], v[180:183], v[236:239], v[8:11]
	v_mfma_f32_16x16x32_bf16 v[60:63], v[136:139], v[216:219], v[60:63]
	v_mfma_f32_16x16x32_bf16 v[56:59], v[184:187], v[216:219], v[56:59]
	v_mfma_f32_16x16x32_bf16 v[44:47], v[136:139], v[224:227], v[44:47]
	v_mfma_f32_16x16x32_bf16 v[40:43], v[184:187], v[224:227], v[40:43]
	v_mfma_f32_16x16x32_bf16 v[28:31], v[136:139], v[232:235], v[28:31]
	v_mfma_f32_16x16x32_bf16 v[24:27], v[184:187], v[232:235], v[24:27]
	v_mfma_f32_16x16x32_bf16 v[12:15], v[136:139], v[240:243], v[12:15]
	v_mfma_f32_16x16x32_bf16 v[8:11], v[184:187], v[240:243], v[8:11]
	v_mfma_f32_16x16x32_bf16 v[52:55], v[196:199], v[212:215], v[52:55]
	v_mfma_f32_16x16x32_bf16 v[48:51], v[204:207], v[212:215], v[48:51]
	v_mfma_f32_16x16x32_bf16 v[36:39], v[196:199], v[220:223], v[36:39]
	v_mfma_f32_16x16x32_bf16 v[32:35], v[204:207], v[220:223], v[32:35]
	v_mfma_f32_16x16x32_bf16 v[20:23], v[196:199], v[228:231], v[20:23]
	v_mfma_f32_16x16x32_bf16 v[16:19], v[204:207], v[228:231], v[16:19]
	v_mfma_f32_16x16x32_bf16 v[4:7], v[196:199], v[236:239], v[4:7]
	v_mfma_f32_16x16x32_bf16 v[0:3], v[204:207], v[236:239], v[0:3]
	v_mfma_f32_16x16x32_bf16 v[52:55], v[200:203], v[216:219], v[52:55]
	v_mfma_f32_16x16x32_bf16 v[48:51], v[208:211], v[216:219], v[48:51]
	v_mfma_f32_16x16x32_bf16 v[36:39], v[200:203], v[224:227], v[36:39]
	v_mfma_f32_16x16x32_bf16 v[32:35], v[208:211], v[224:227], v[32:35]
	v_mfma_f32_16x16x32_bf16 v[20:23], v[200:203], v[232:235], v[20:23]
	v_mfma_f32_16x16x32_bf16 v[16:19], v[208:211], v[232:235], v[16:19]
	v_mfma_f32_16x16x32_bf16 v[4:7], v[200:203], v[240:243], v[4:7]
	v_mfma_f32_16x16x32_bf16 v[0:3], v[208:211], v[240:243], v[0:3]
	s_barrier
	s_add_u32 s23, s23, 0x100
	s_addc_u32 s72, s72, 0
	s_add_u32 s73, s73, 0x100
	s_addc_u32 s74, s74, 0
	s_cmp_lt_i32 s22, s26
	s_cbranch_scc1 .LBB0_962

.LBB0_1036:
	s_add_u32 s18, vcc_lo, 0xfff80080
	s_addc_u32 s19, vcc_hi, -1
	s_add_i32 s81, 0, 0x10000
	s_cmp_eq_u32 s80, 28
	s_cselect_b32 s59, s51, s19
	s_cselect_b32 s58, s76, s18
	s_cselect_b32 s19, s49, s79
	s_cselect_b32 s18, s77, s78
	s_add_i32 s84, 0, 0x14000
	v_add_u32_e32 v168, s81, v145
	v_add_u32_e32 v184, s84, v145
	ds_read_b128 v[140:143], v168
	ds_read_b128 v[150:153], v168 offset:1024
	ds_read_b128 v[154:157], v168 offset:2048
	ds_read_b128 v[168:171], v168 offset:3072
	ds_read_b128 v[172:175], v184
	ds_read_b128 v[176:179], v184 offset:1024
	ds_read_b128 v[180:183], v184 offset:2048
	ds_read_b128 v[184:187], v184 offset:3072
	v_lshl_add_u64 v[192:193], vcc, 0, v[138:139]
	s_add_i32 m0, s67, 0xc000
	ds_read_b128 v[188:191], v149
	ds_read_b128 v[196:199], v149 offset:1024
	ds_read_b128 v[200:203], v149 offset:2048
	ds_read_b128 v[204:207], v149 offset:3072
	ds_read_b128 v[208:211], v149 offset:4096
	ds_read_b128 v[212:215], v149 offset:5120
	ds_read_b128 v[216:219], v149 offset:6144
	ds_read_b128 v[220:223], v149 offset:7168
	global_load_lds_dwordx4 v[192:193], off
	v_lshl_add_u64 v[192:193], vcc, 0, v[136:137]
	s_add_i32 m0, s67, 0xe000
	s_nop 0
	global_load_lds_dwordx4 v[192:193], off
	s_waitcnt vmcnt(8)
	s_waitcnt lgkmcnt(0)
	s_barrier
	s_waitcnt lgkmcnt(0)
	v_mfma_f32_16x16x32_bf16 v[126:129], v[140:143], v[188:191], v[126:129]
	v_mfma_f32_16x16x32_bf16 v[122:125], v[154:157], v[188:191], v[122:125]
	v_mfma_f32_16x16x32_bf16 v[110:113], v[140:143], v[200:203], v[110:113]
	v_mfma_f32_16x16x32_bf16 v[106:109], v[154:157], v[200:203], v[106:109]
	v_mfma_f32_16x16x32_bf16 v[92:95], v[140:143], v[208:211], v[92:95]
	v_mfma_f32_16x16x32_bf16 v[88:91], v[154:157], v[208:211], v[88:91]
	v_mfma_f32_16x16x32_bf16 v[76:79], v[140:143], v[216:219], v[76:79]
	v_mfma_f32_16x16x32_bf16 v[72:75], v[154:157], v[216:219], v[72:75]
	v_mfma_f32_16x16x32_bf16 v[126:129], v[150:153], v[196:199], v[126:129]
	v_mfma_f32_16x16x32_bf16 v[122:125], v[168:171], v[196:199], v[122:125]
	v_mfma_f32_16x16x32_bf16 v[110:113], v[150:153], v[204:207], v[110:113]
	v_mfma_f32_16x16x32_bf16 v[106:109], v[168:171], v[204:207], v[106:109]
	v_mfma_f32_16x16x32_bf16 v[92:95], v[150:153], v[212:215], v[92:95]
	v_mfma_f32_16x16x32_bf16 v[88:91], v[168:171], v[212:215], v[88:91]
	v_mfma_f32_16x16x32_bf16 v[76:79], v[150:153], v[220:223], v[76:79]
	v_mfma_f32_16x16x32_bf16 v[72:75], v[168:171], v[220:223], v[72:75]
	v_mfma_f32_16x16x32_bf16 v[118:121], v[172:175], v[188:191], v[118:121]
	v_mfma_f32_16x16x32_bf16 v[114:117], v[180:183], v[188:191], v[114:117]
	v_mfma_f32_16x16x32_bf16 v[102:105], v[172:175], v[200:203], v[102:105]
	v_mfma_f32_16x16x32_bf16 v[98:101], v[180:183], v[200:203], v[98:101]
	v_mfma_f32_16x16x32_bf16 v[84:87], v[172:175], v[208:211], v[84:87]
	v_mfma_f32_16x16x32_bf16 v[80:83], v[180:183], v[208:211], v[80:83]
	v_mfma_f32_16x16x32_bf16 v[68:71], v[172:175], v[216:219], v[68:71]
	v_mfma_f32_16x16x32_bf16 v[64:67], v[180:183], v[216:219], v[64:67]
	v_mfma_f32_16x16x32_bf16 v[118:121], v[176:179], v[196:199], v[118:121]
	v_mfma_f32_16x16x32_bf16 v[114:117], v[184:187], v[196:199], v[114:117]
	v_mfma_f32_16x16x32_bf16 v[102:105], v[176:179], v[204:207], v[102:105]
	v_mfma_f32_16x16x32_bf16 v[98:101], v[184:187], v[204:207], v[98:101]
	v_mfma_f32_16x16x32_bf16 v[84:87], v[176:179], v[212:215], v[84:87]
	v_mfma_f32_16x16x32_bf16 v[80:83], v[184:187], v[212:215], v[80:83]
	v_mfma_f32_16x16x32_bf16 v[68:71], v[176:179], v[220:223], v[68:71]
	v_mfma_f32_16x16x32_bf16 v[64:67], v[184:187], v[220:223], v[64:67]
	s_barrier
	s_add_i32 s81, s81, s66
	v_lshl_add_u64 v[192:193], s[18:19], 0, v[96:97]
	s_mov_b32 m0, s81
	ds_read_b128 v[188:191], v149 offset:16384
	ds_read_b128 v[196:199], v149 offset:17408
	ds_read_b128 v[200:203], v149 offset:18432
	ds_read_b128 v[204:207], v149 offset:19456
	ds_read_b128 v[208:211], v149 offset:20480
	ds_read_b128 v[212:215], v149 offset:21504
	ds_read_b128 v[216:219], v149 offset:22528
	ds_read_b128 v[220:223], v149 offset:23552
	global_load_lds_dwordx4 v[192:193], off
	s_add_i32 m0, s81, 0x2000
	s_add_u32 s82, s18, 0x80000
	v_lshl_add_u64 v[224:225], s[18:19], 0, v[130:131]
	s_addc_u32 s83, s19, 0
	s_add_i32 s81, s84, s66
	global_load_lds_dwordx4 v[224:225], off
	v_lshl_add_u64 v[226:227], s[82:83], 0, v[96:97]
	s_mov_b32 m0, s81
	v_lshl_add_u64 v[228:229], s[58:59], 0, v[132:133]
	global_load_lds_dwordx4 v[226:227], off
	v_lshl_add_u64 v[226:227], s[82:83], 0, v[130:131]
	s_add_i32 m0, s81, 0x2000
	s_nop 0
	global_load_lds_dwordx4 v[226:227], off
	v_lshl_add_u64 v[226:227], s[58:59], 0, v[134:135]
	s_mov_b32 m0, s67
	s_nop 0
	global_load_lds_dwordx4 v[226:227], off
	s_mov_b32 m0, s68
	s_nop 0
	global_load_lds_dwordx4 v[228:229], off
	s_waitcnt vmcnt(8)
	s_waitcnt lgkmcnt(0)
	s_barrier
	s_waitcnt lgkmcnt(0)
	v_mfma_f32_16x16x32_bf16 v[60:63], v[140:143], v[188:191], v[60:63]
	v_mfma_f32_16x16x32_bf16 v[56:59], v[154:157], v[188:191], v[56:59]
	v_mfma_f32_16x16x32_bf16 v[44:47], v[140:143], v[200:203], v[44:47]
	v_mfma_f32_16x16x32_bf16 v[40:43], v[154:157], v[200:203], v[40:43]
	v_mfma_f32_16x16x32_bf16 v[28:31], v[140:143], v[208:211], v[28:31]
	v_mfma_f32_16x16x32_bf16 v[24:27], v[154:157], v[208:211], v[24:27]
	v_mfma_f32_16x16x32_bf16 v[12:15], v[140:143], v[216:219], v[12:15]
	v_mfma_f32_16x16x32_bf16 v[8:11], v[154:157], v[216:219], v[8:11]
	v_mfma_f32_16x16x32_bf16 v[60:63], v[150:153], v[196:199], v[60:63]
	v_mfma_f32_16x16x32_bf16 v[56:59], v[168:171], v[196:199], v[56:59]
	v_mfma_f32_16x16x32_bf16 v[44:47], v[150:153], v[204:207], v[44:47]
	v_mfma_f32_16x16x32_bf16 v[40:43], v[168:171], v[204:207], v[40:43]
	v_mfma_f32_16x16x32_bf16 v[28:31], v[150:153], v[212:215], v[28:31]
	v_mfma_f32_16x16x32_bf16 v[24:27], v[168:171], v[212:215], v[24:27]
	v_mfma_f32_16x16x32_bf16 v[12:15], v[150:153], v[220:223], v[12:15]
	v_mfma_f32_16x16x32_bf16 v[8:11], v[168:171], v[220:223], v[8:11]
	v_mfma_f32_16x16x32_bf16 v[52:55], v[172:175], v[188:191], v[52:55]
	v_mfma_f32_16x16x32_bf16 v[48:51], v[180:183], v[188:191], v[48:51]
	v_mfma_f32_16x16x32_bf16 v[36:39], v[172:175], v[200:203], v[36:39]
	v_mfma_f32_16x16x32_bf16 v[32:35], v[180:183], v[200:203], v[32:35]
	v_mfma_f32_16x16x32_bf16 v[20:23], v[172:175], v[208:211], v[20:23]
	v_mfma_f32_16x16x32_bf16 v[16:19], v[180:183], v[208:211], v[16:19]
	v_mfma_f32_16x16x32_bf16 v[4:7], v[172:175], v[216:219], v[4:7]
	v_mfma_f32_16x16x32_bf16 v[0:3], v[180:183], v[216:219], v[0:3]
	v_mfma_f32_16x16x32_bf16 v[52:55], v[176:179], v[196:199], v[52:55]
	v_mfma_f32_16x16x32_bf16 v[48:51], v[184:187], v[196:199], v[48:51]
	v_mfma_f32_16x16x32_bf16 v[36:39], v[176:179], v[204:207], v[36:39]
	v_mfma_f32_16x16x32_bf16 v[32:35], v[184:187], v[204:207], v[32:35]
	v_mfma_f32_16x16x32_bf16 v[20:23], v[176:179], v[212:215], v[20:23]
	v_mfma_f32_16x16x32_bf16 v[16:19], v[184:187], v[212:215], v[16:19]
	v_mfma_f32_16x16x32_bf16 v[4:7], v[176:179], v[220:223], v[4:7]
	v_mfma_f32_16x16x32_bf16 v[0:3], v[184:187], v[220:223], v[0:3]
	s_barrier
	s_add_i32 s81, 0, 0x18000
	s_add_i32 s82, 0, 0x1c000
	v_add_u32_e32 v168, s81, v145
	v_add_u32_e32 v184, s82, v145
	ds_read_b128 v[140:143], v168
	ds_read_b128 v[150:153], v168 offset:1024
	ds_read_b128 v[154:157], v168 offset:2048
	ds_read_b128 v[168:171], v168 offset:3072
	ds_read_b128 v[172:175], v184
	ds_read_b128 v[176:179], v184 offset:1024
	ds_read_b128 v[180:183], v184 offset:2048
	ds_read_b128 v[184:187], v184 offset:3072
	s_add_u32 s58, s58, 0x80000
	s_addc_u32 s59, s59, 0
	s_mov_b32 m0, s69
	v_lshl_add_u64 v[230:231], s[58:59], 0, v[134:135]
	ds_read_b128 v[188:191], v149 offset:32768
	ds_read_b128 v[196:199], v149 offset:33792
	ds_read_b128 v[200:203], v149 offset:34816
	ds_read_b128 v[204:207], v149 offset:35840
	ds_read_b128 v[208:211], v149 offset:36864
	ds_read_b128 v[212:215], v149 offset:37888
	ds_read_b128 v[216:219], v149 offset:38912
	ds_read_b128 v[220:223], v149 offset:39936
	global_load_lds_dwordx4 v[230:231], off
	v_lshl_add_u64 v[230:231], s[58:59], 0, v[132:133]
	s_mov_b32 m0, s70
	s_nop 0
	global_load_lds_dwordx4 v[230:231], off
	s_waitcnt vmcnt(8)
	s_waitcnt lgkmcnt(0)
	s_barrier
	s_waitcnt lgkmcnt(0)
	v_mfma_f32_16x16x32_bf16 v[126:129], v[140:143], v[188:191], v[126:129]
	v_mfma_f32_16x16x32_bf16 v[122:125], v[154:157], v[188:191], v[122:125]
	v_mfma_f32_16x16x32_bf16 v[110:113], v[140:143], v[200:203], v[110:113]
	v_mfma_f32_16x16x32_bf16 v[106:109], v[154:157], v[200:203], v[106:109]
	v_mfma_f32_16x16x32_bf16 v[92:95], v[140:143], v[208:211], v[92:95]
	v_mfma_f32_16x16x32_bf16 v[88:91], v[154:157], v[208:211], v[88:91]
	v_mfma_f32_16x16x32_bf16 v[76:79], v[140:143], v[216:219], v[76:79]
	v_mfma_f32_16x16x32_bf16 v[72:75], v[154:157], v[216:219], v[72:75]
	v_mfma_f32_16x16x32_bf16 v[126:129], v[150:153], v[196:199], v[126:129]
	v_mfma_f32_16x16x32_bf16 v[122:125], v[168:171], v[196:199], v[122:125]
	v_mfma_f32_16x16x32_bf16 v[110:113], v[150:153], v[204:207], v[110:113]
	v_mfma_f32_16x16x32_bf16 v[106:109], v[168:171], v[204:207], v[106:109]
	v_mfma_f32_16x16x32_bf16 v[92:95], v[150:153], v[212:215], v[92:95]
	v_mfma_f32_16x16x32_bf16 v[88:91], v[168:171], v[212:215], v[88:91]
	v_mfma_f32_16x16x32_bf16 v[76:79], v[150:153], v[220:223], v[76:79]
	v_mfma_f32_16x16x32_bf16 v[72:75], v[168:171], v[220:223], v[72:75]
	v_mfma_f32_16x16x32_bf16 v[118:121], v[172:175], v[188:191], v[118:121]
	v_mfma_f32_16x16x32_bf16 v[114:117], v[180:183], v[188:191], v[114:117]
	v_mfma_f32_16x16x32_bf16 v[102:105], v[172:175], v[200:203], v[102:105]
	v_mfma_f32_16x16x32_bf16 v[98:101], v[180:183], v[200:203], v[98:101]
	v_mfma_f32_16x16x32_bf16 v[84:87], v[172:175], v[208:211], v[84:87]
	v_mfma_f32_16x16x32_bf16 v[80:83], v[180:183], v[208:211], v[80:83]
	v_mfma_f32_16x16x32_bf16 v[68:71], v[172:175], v[216:219], v[68:71]
	v_mfma_f32_16x16x32_bf16 v[64:67], v[180:183], v[216:219], v[64:67]
	v_mfma_f32_16x16x32_bf16 v[118:121], v[176:179], v[196:199], v[118:121]
	v_mfma_f32_16x16x32_bf16 v[114:117], v[184:187], v[196:199], v[114:117]
	v_mfma_f32_16x16x32_bf16 v[102:105], v[176:179], v[204:207], v[102:105]
	v_mfma_f32_16x16x32_bf16 v[98:101], v[184:187], v[204:207], v[98:101]
	v_mfma_f32_16x16x32_bf16 v[84:87], v[176:179], v[212:215], v[84:87]
	v_mfma_f32_16x16x32_bf16 v[80:83], v[184:187], v[212:215], v[80:83]
	v_mfma_f32_16x16x32_bf16 v[68:71], v[176:179], v[220:223], v[68:71]
	v_mfma_f32_16x16x32_bf16 v[64:67], v[184:187], v[220:223], v[64:67]
	s_barrier
	s_add_i32 s58, s81, s66
	v_lshl_add_u64 v[192:193], v[192:193], 0, s[30:31]
	s_mov_b32 m0, s58
	ds_read_b128 v[188:191], v149 offset:49152
	ds_read_b128 v[196:199], v149 offset:50176
	ds_read_b128 v[200:203], v149 offset:51200
	ds_read_b128 v[204:207], v149 offset:52224
	ds_read_b128 v[208:211], v149 offset:53248
	ds_read_b128 v[212:215], v149 offset:54272
	ds_read_b128 v[216:219], v149 offset:55296
	ds_read_b128 v[220:223], v149 offset:56320
	global_load_lds_dwordx4 v[192:193], off
	s_add_i32 m0, s58, 0x2000
	s_add_u32 s18, s18, 0x80080
	v_lshl_add_u64 v[192:193], v[224:225], 0, s[30:31]
	s_addc_u32 s19, s19, 0
	s_add_i32 s58, s82, s66
	global_load_lds_dwordx4 v[192:193], off
	v_lshl_add_u64 v[192:193], s[18:19], 0, v[96:97]
	s_mov_b32 m0, s58
	s_nop 0
	global_load_lds_dwordx4 v[192:193], off
	v_lshl_add_u64 v[192:193], s[18:19], 0, v[130:131]
	s_add_i32 m0, s58, 0x2000
	s_nop 0
	global_load_lds_dwordx4 v[192:193], off
	v_lshl_add_u64 v[192:193], v[226:227], 0, s[30:31]
	s_mov_b32 m0, s71
	s_nop 0
	global_load_lds_dwordx4 v[192:193], off
	v_lshl_add_u64 v[192:193], v[228:229], 0, s[30:31]
	s_mov_b32 m0, s72
	s_nop 0
	global_load_lds_dwordx4 v[192:193], off
	s_waitcnt vmcnt(8)
	s_waitcnt lgkmcnt(0)
	s_barrier
	s_waitcnt lgkmcnt(0)
	v_mfma_f32_16x16x32_bf16 v[60:63], v[140:143], v[188:191], v[60:63]
	v_mfma_f32_16x16x32_bf16 v[56:59], v[154:157], v[188:191], v[56:59]
	v_mfma_f32_16x16x32_bf16 v[44:47], v[140:143], v[200:203], v[44:47]
	v_mfma_f32_16x16x32_bf16 v[40:43], v[154:157], v[200:203], v[40:43]
	v_mfma_f32_16x16x32_bf16 v[28:31], v[140:143], v[208:211], v[28:31]
	v_mfma_f32_16x16x32_bf16 v[24:27], v[154:157], v[208:211], v[24:27]
	v_mfma_f32_16x16x32_bf16 v[12:15], v[140:143], v[216:219], v[12:15]
	v_mfma_f32_16x16x32_bf16 v[8:11], v[154:157], v[216:219], v[8:11]
	v_mfma_f32_16x16x32_bf16 v[60:63], v[150:153], v[196:199], v[60:63]
	v_mfma_f32_16x16x32_bf16 v[56:59], v[168:171], v[196:199], v[56:59]
	v_mfma_f32_16x16x32_bf16 v[44:47], v[150:153], v[204:207], v[44:47]
	v_mfma_f32_16x16x32_bf16 v[40:43], v[168:171], v[204:207], v[40:43]
	v_mfma_f32_16x16x32_bf16 v[28:31], v[150:153], v[212:215], v[28:31]
	v_mfma_f32_16x16x32_bf16 v[24:27], v[168:171], v[212:215], v[24:27]
	v_mfma_f32_16x16x32_bf16 v[12:15], v[150:153], v[220:223], v[12:15]
	v_mfma_f32_16x16x32_bf16 v[8:11], v[168:171], v[220:223], v[8:11]
	v_mfma_f32_16x16x32_bf16 v[52:55], v[172:175], v[188:191], v[52:55]
	v_mfma_f32_16x16x32_bf16 v[48:51], v[180:183], v[188:191], v[48:51]
	v_mfma_f32_16x16x32_bf16 v[36:39], v[172:175], v[200:203], v[36:39]
	v_mfma_f32_16x16x32_bf16 v[32:35], v[180:183], v[200:203], v[32:35]
	v_mfma_f32_16x16x32_bf16 v[20:23], v[172:175], v[208:211], v[20:23]
	v_mfma_f32_16x16x32_bf16 v[16:19], v[180:183], v[208:211], v[16:19]
	v_mfma_f32_16x16x32_bf16 v[4:7], v[172:175], v[216:219], v[4:7]
	v_mfma_f32_16x16x32_bf16 v[0:3], v[180:183], v[216:219], v[0:3]
	v_mfma_f32_16x16x32_bf16 v[52:55], v[176:179], v[196:199], v[52:55]
	v_mfma_f32_16x16x32_bf16 v[48:51], v[184:187], v[196:199], v[48:51]
	v_mfma_f32_16x16x32_bf16 v[36:39], v[176:179], v[204:207], v[36:39]
	v_mfma_f32_16x16x32_bf16 v[32:35], v[184:187], v[204:207], v[32:35]
	v_mfma_f32_16x16x32_bf16 v[20:23], v[176:179], v[212:215], v[20:23]
	v_mfma_f32_16x16x32_bf16 v[16:19], v[184:187], v[212:215], v[16:19]
	v_mfma_f32_16x16x32_bf16 v[4:7], v[176:179], v[220:223], v[4:7]
	v_mfma_f32_16x16x32_bf16 v[0:3], v[184:187], v[220:223], v[0:3]
	s_barrier
	s_add_i32 s80, s80, 2
	s_add_u32 s78, s78, 0x100
	s_addc_u32 s79, s79, 0
	s_add_u32 vcc_lo, vcc_lo, 0x100
	s_addc_u32 vcc_hi, vcc_hi, 0
	s_cmp_gt_u32 s80, 29
	s_cbranch_scc0 .LBB0_1036
	s_and_b64 vcc, exec, s[24:25]
	s_cbranch_vccz .LBB0_1039
	s_barrier

.LBB0_1124:
	s_add_u32 s18, s58, 0xfff80080
	s_addc_u32 s19, s59, -1
	s_add_i32 s79, 0, 0x10000
	s_cmp_eq_u32 s78, 28
	s_cselect_b32 s35, s43, s19
	s_cselect_b32 s34, s74, s18
	v_add_u32_e32 v156, s79, v149
	s_cselect_b32 s19, s37, s77
	s_cselect_b32 s18, s75, s76
	s_add_i32 s82, 0, 0x14000
	ds_read_b128 v[140:143], v156
	ds_read_b128 v[144:147], v156 offset:1024
	ds_read_b128 v[152:155], v156 offset:2048
	ds_read_b128 v[168:171], v156 offset:3072
	v_add_u32_e32 v156, s82, v149
	ds_read_b128 v[172:175], v156
	ds_read_b128 v[176:179], v156 offset:1024
	ds_read_b128 v[180:183], v156 offset:2048
	ds_read_b128 v[184:187], v156 offset:3072
	v_lshl_add_u64 v[156:157], s[58:59], 0, v[138:139]
	s_add_i32 m0, s65, 0xc000
	ds_read_b128 v[188:191], v151
	ds_read_b128 v[196:199], v151 offset:1024
	ds_read_b128 v[200:203], v151 offset:2048
	ds_read_b128 v[204:207], v151 offset:3072
	ds_read_b128 v[208:211], v151 offset:4096
	ds_read_b128 v[212:215], v151 offset:5120
	ds_read_b128 v[216:219], v151 offset:6144
	ds_read_b128 v[220:223], v151 offset:7168
	global_load_lds_dwordx4 v[156:157], off
	v_lshl_add_u64 v[156:157], s[58:59], 0, v[136:137]
	s_add_i32 m0, s65, 0xe000
	s_nop 0
	global_load_lds_dwordx4 v[156:157], off
	s_waitcnt vmcnt(8)
	s_waitcnt lgkmcnt(0)
	s_barrier
	s_waitcnt lgkmcnt(0)
	v_mfma_f32_16x16x32_bf16 v[126:129], v[140:143], v[188:191], v[126:129]
	v_mfma_f32_16x16x32_bf16 v[122:125], v[152:155], v[188:191], v[122:125]
	v_mfma_f32_16x16x32_bf16 v[110:113], v[140:143], v[200:203], v[110:113]
	v_mfma_f32_16x16x32_bf16 v[106:109], v[152:155], v[200:203], v[106:109]
	v_mfma_f32_16x16x32_bf16 v[92:95], v[140:143], v[208:211], v[92:95]
	v_mfma_f32_16x16x32_bf16 v[88:91], v[152:155], v[208:211], v[88:91]
	v_mfma_f32_16x16x32_bf16 v[76:79], v[140:143], v[216:219], v[76:79]
	v_mfma_f32_16x16x32_bf16 v[72:75], v[152:155], v[216:219], v[72:75]
	v_mfma_f32_16x16x32_bf16 v[126:129], v[144:147], v[196:199], v[126:129]
	v_mfma_f32_16x16x32_bf16 v[122:125], v[168:171], v[196:199], v[122:125]
	v_mfma_f32_16x16x32_bf16 v[110:113], v[144:147], v[204:207], v[110:113]
	v_mfma_f32_16x16x32_bf16 v[106:109], v[168:171], v[204:207], v[106:109]
	v_mfma_f32_16x16x32_bf16 v[92:95], v[144:147], v[212:215], v[92:95]
	v_mfma_f32_16x16x32_bf16 v[88:91], v[168:171], v[212:215], v[88:91]
	v_mfma_f32_16x16x32_bf16 v[76:79], v[144:147], v[220:223], v[76:79]
	v_mfma_f32_16x16x32_bf16 v[72:75], v[168:171], v[220:223], v[72:75]
	v_mfma_f32_16x16x32_bf16 v[118:121], v[172:175], v[188:191], v[118:121]
	v_mfma_f32_16x16x32_bf16 v[114:117], v[180:183], v[188:191], v[114:117]
	v_mfma_f32_16x16x32_bf16 v[102:105], v[172:175], v[200:203], v[102:105]
	v_mfma_f32_16x16x32_bf16 v[98:101], v[180:183], v[200:203], v[98:101]
	v_mfma_f32_16x16x32_bf16 v[84:87], v[172:175], v[208:211], v[84:87]
	v_mfma_f32_16x16x32_bf16 v[80:83], v[180:183], v[208:211], v[80:83]
	v_mfma_f32_16x16x32_bf16 v[68:71], v[172:175], v[216:219], v[68:71]
	v_mfma_f32_16x16x32_bf16 v[64:67], v[180:183], v[216:219], v[64:67]
	v_mfma_f32_16x16x32_bf16 v[118:121], v[176:179], v[196:199], v[118:121]
	v_mfma_f32_16x16x32_bf16 v[114:117], v[184:187], v[196:199], v[114:117]
	v_mfma_f32_16x16x32_bf16 v[102:105], v[176:179], v[204:207], v[102:105]
	v_mfma_f32_16x16x32_bf16 v[98:101], v[184:187], v[204:207], v[98:101]
	v_mfma_f32_16x16x32_bf16 v[84:87], v[176:179], v[212:215], v[84:87]
	v_mfma_f32_16x16x32_bf16 v[80:83], v[184:187], v[212:215], v[80:83]
	v_mfma_f32_16x16x32_bf16 v[68:71], v[176:179], v[220:223], v[68:71]
	v_mfma_f32_16x16x32_bf16 v[64:67], v[184:187], v[220:223], v[64:67]
	s_barrier
	s_add_i32 s79, s79, s61
	v_lshl_add_u64 v[156:157], s[18:19], 0, v[96:97]
	s_mov_b32 m0, s79
	ds_read_b128 v[188:191], v151 offset:16384
	ds_read_b128 v[196:199], v151 offset:17408
	ds_read_b128 v[200:203], v151 offset:18432
	ds_read_b128 v[204:207], v151 offset:19456
	ds_read_b128 v[208:211], v151 offset:20480
	ds_read_b128 v[212:215], v151 offset:21504
	ds_read_b128 v[216:219], v151 offset:22528
	ds_read_b128 v[220:223], v151 offset:23552
	global_load_lds_dwordx4 v[156:157], off
	s_add_i32 m0, s79, 0x2000
	s_add_u32 s80, s18, 0x80000
	v_lshl_add_u64 v[192:193], s[18:19], 0, v[130:131]
	s_addc_u32 s81, s19, 0
	s_add_i32 s79, s82, s61
	global_load_lds_dwordx4 v[192:193], off
	v_lshl_add_u64 v[224:225], s[80:81], 0, v[96:97]
	s_mov_b32 m0, s79
	v_lshl_add_u64 v[226:227], s[34:35], 0, v[132:133]
	global_load_lds_dwordx4 v[224:225], off
	v_lshl_add_u64 v[224:225], s[80:81], 0, v[130:131]
	s_add_i32 m0, s79, 0x2000
	s_nop 0
	global_load_lds_dwordx4 v[224:225], off
	v_lshl_add_u64 v[224:225], s[34:35], 0, v[134:135]
	s_mov_b32 m0, s65
	s_nop 0
	global_load_lds_dwordx4 v[224:225], off
	s_mov_b32 m0, s66
	s_nop 0
	global_load_lds_dwordx4 v[226:227], off
	s_waitcnt vmcnt(8)
	s_waitcnt lgkmcnt(0)
	s_barrier
	s_waitcnt lgkmcnt(0)
	v_mfma_f32_16x16x32_bf16 v[60:63], v[140:143], v[188:191], v[60:63]
	v_mfma_f32_16x16x32_bf16 v[56:59], v[152:155], v[188:191], v[56:59]
	v_mfma_f32_16x16x32_bf16 v[44:47], v[140:143], v[200:203], v[44:47]
	v_mfma_f32_16x16x32_bf16 v[40:43], v[152:155], v[200:203], v[40:43]
	v_mfma_f32_16x16x32_bf16 v[28:31], v[140:143], v[208:211], v[28:31]
	v_mfma_f32_16x16x32_bf16 v[24:27], v[152:155], v[208:211], v[24:27]
	v_mfma_f32_16x16x32_bf16 v[12:15], v[140:143], v[216:219], v[12:15]
	v_mfma_f32_16x16x32_bf16 v[8:11], v[152:155], v[216:219], v[8:11]
	v_mfma_f32_16x16x32_bf16 v[60:63], v[144:147], v[196:199], v[60:63]
	v_mfma_f32_16x16x32_bf16 v[56:59], v[168:171], v[196:199], v[56:59]
	v_mfma_f32_16x16x32_bf16 v[44:47], v[144:147], v[204:207], v[44:47]
	v_mfma_f32_16x16x32_bf16 v[40:43], v[168:171], v[204:207], v[40:43]
	v_mfma_f32_16x16x32_bf16 v[28:31], v[144:147], v[212:215], v[28:31]
	v_mfma_f32_16x16x32_bf16 v[24:27], v[168:171], v[212:215], v[24:27]
	v_mfma_f32_16x16x32_bf16 v[12:15], v[144:147], v[220:223], v[12:15]
	v_mfma_f32_16x16x32_bf16 v[8:11], v[168:171], v[220:223], v[8:11]
	v_mfma_f32_16x16x32_bf16 v[52:55], v[172:175], v[188:191], v[52:55]
	v_mfma_f32_16x16x32_bf16 v[48:51], v[180:183], v[188:191], v[48:51]
	v_mfma_f32_16x16x32_bf16 v[36:39], v[172:175], v[200:203], v[36:39]
	v_mfma_f32_16x16x32_bf16 v[32:35], v[180:183], v[200:203], v[32:35]
	v_mfma_f32_16x16x32_bf16 v[20:23], v[172:175], v[208:211], v[20:23]
	v_mfma_f32_16x16x32_bf16 v[16:19], v[180:183], v[208:211], v[16:19]
	v_mfma_f32_16x16x32_bf16 v[4:7], v[172:175], v[216:219], v[4:7]
	v_mfma_f32_16x16x32_bf16 v[0:3], v[180:183], v[216:219], v[0:3]
	v_mfma_f32_16x16x32_bf16 v[52:55], v[176:179], v[196:199], v[52:55]
	v_mfma_f32_16x16x32_bf16 v[48:51], v[184:187], v[196:199], v[48:51]
	v_mfma_f32_16x16x32_bf16 v[36:39], v[176:179], v[204:207], v[36:39]
	v_mfma_f32_16x16x32_bf16 v[32:35], v[184:187], v[204:207], v[32:35]
	v_mfma_f32_16x16x32_bf16 v[20:23], v[176:179], v[212:215], v[20:23]
	v_mfma_f32_16x16x32_bf16 v[16:19], v[184:187], v[212:215], v[16:19]
	v_mfma_f32_16x16x32_bf16 v[4:7], v[176:179], v[220:223], v[4:7]
	v_mfma_f32_16x16x32_bf16 v[0:3], v[184:187], v[220:223], v[0:3]
	s_barrier
	s_add_i32 s79, 0, 0x18000
	s_add_i32 s80, 0, 0x1c000
	v_add_u32_e32 v168, s79, v149
	v_add_u32_e32 v184, s80, v149
	ds_read_b128 v[140:143], v168
	ds_read_b128 v[144:147], v168 offset:1024
	ds_read_b128 v[152:155], v168 offset:2048
	ds_read_b128 v[168:171], v168 offset:3072
	ds_read_b128 v[172:175], v184
	ds_read_b128 v[176:179], v184 offset:1024
	ds_read_b128 v[180:183], v184 offset:2048
	ds_read_b128 v[184:187], v184 offset:3072
	s_add_u32 s34, s34, 0x80000
	s_addc_u32 s35, s35, 0
	s_mov_b32 m0, s67
	v_lshl_add_u64 v[228:229], s[34:35], 0, v[134:135]
	ds_read_b128 v[188:191], v151 offset:32768
	ds_read_b128 v[196:199], v151 offset:33792
	ds_read_b128 v[200:203], v151 offset:34816
	ds_read_b128 v[204:207], v151 offset:35840
	ds_read_b128 v[208:211], v151 offset:36864
	ds_read_b128 v[212:215], v151 offset:37888
	ds_read_b128 v[216:219], v151 offset:38912
	ds_read_b128 v[220:223], v151 offset:39936
	global_load_lds_dwordx4 v[228:229], off
	v_lshl_add_u64 v[228:229], s[34:35], 0, v[132:133]
	s_mov_b32 m0, s68
	s_nop 0
	global_load_lds_dwordx4 v[228:229], off
	s_waitcnt vmcnt(8)
	s_waitcnt lgkmcnt(0)
	s_barrier
	s_waitcnt lgkmcnt(0)
	v_mfma_f32_16x16x32_bf16 v[126:129], v[140:143], v[188:191], v[126:129]
	v_mfma_f32_16x16x32_bf16 v[122:125], v[152:155], v[188:191], v[122:125]
	v_mfma_f32_16x16x32_bf16 v[110:113], v[140:143], v[200:203], v[110:113]
	v_mfma_f32_16x16x32_bf16 v[106:109], v[152:155], v[200:203], v[106:109]
	v_mfma_f32_16x16x32_bf16 v[92:95], v[140:143], v[208:211], v[92:95]
	v_mfma_f32_16x16x32_bf16 v[88:91], v[152:155], v[208:211], v[88:91]
	v_mfma_f32_16x16x32_bf16 v[76:79], v[140:143], v[216:219], v[76:79]
	v_mfma_f32_16x16x32_bf16 v[72:75], v[152:155], v[216:219], v[72:75]
	v_mfma_f32_16x16x32_bf16 v[126:129], v[144:147], v[196:199], v[126:129]
	v_mfma_f32_16x16x32_bf16 v[122:125], v[168:171], v[196:199], v[122:125]
	v_mfma_f32_16x16x32_bf16 v[110:113], v[144:147], v[204:207], v[110:113]
	v_mfma_f32_16x16x32_bf16 v[106:109], v[168:171], v[204:207], v[106:109]
	v_mfma_f32_16x16x32_bf16 v[92:95], v[144:147], v[212:215], v[92:95]
	v_mfma_f32_16x16x32_bf16 v[88:91], v[168:171], v[212:215], v[88:91]
	v_mfma_f32_16x16x32_bf16 v[76:79], v[144:147], v[220:223], v[76:79]
	v_mfma_f32_16x16x32_bf16 v[72:75], v[168:171], v[220:223], v[72:75]
	v_mfma_f32_16x16x32_bf16 v[118:121], v[172:175], v[188:191], v[118:121]
	v_mfma_f32_16x16x32_bf16 v[114:117], v[180:183], v[188:191], v[114:117]
	v_mfma_f32_16x16x32_bf16 v[102:105], v[172:175], v[200:203], v[102:105]
	v_mfma_f32_16x16x32_bf16 v[98:101], v[180:183], v[200:203], v[98:101]
	v_mfma_f32_16x16x32_bf16 v[84:87], v[172:175], v[208:211], v[84:87]
	v_mfma_f32_16x16x32_bf16 v[80:83], v[180:183], v[208:211], v[80:83]
	v_mfma_f32_16x16x32_bf16 v[68:71], v[172:175], v[216:219], v[68:71]
	v_mfma_f32_16x16x32_bf16 v[64:67], v[180:183], v[216:219], v[64:67]
	v_mfma_f32_16x16x32_bf16 v[118:121], v[176:179], v[196:199], v[118:121]
	v_mfma_f32_16x16x32_bf16 v[114:117], v[184:187], v[196:199], v[114:117]
	v_mfma_f32_16x16x32_bf16 v[102:105], v[176:179], v[204:207], v[102:105]
	v_mfma_f32_16x16x32_bf16 v[98:101], v[184:187], v[204:207], v[98:101]
	v_mfma_f32_16x16x32_bf16 v[84:87], v[176:179], v[212:215], v[84:87]
	v_mfma_f32_16x16x32_bf16 v[80:83], v[184:187], v[212:215], v[80:83]
	v_mfma_f32_16x16x32_bf16 v[68:71], v[176:179], v[220:223], v[68:71]
	v_mfma_f32_16x16x32_bf16 v[64:67], v[184:187], v[220:223], v[64:67]
	s_barrier
	s_add_i32 s34, s79, s61
	v_lshl_add_u64 v[156:157], v[156:157], 0, s[30:31]
	s_mov_b32 m0, s34
	ds_read_b128 v[188:191], v151 offset:49152
	ds_read_b128 v[196:199], v151 offset:50176
	ds_read_b128 v[200:203], v151 offset:51200
	ds_read_b128 v[204:207], v151 offset:52224
	ds_read_b128 v[208:211], v151 offset:53248
	ds_read_b128 v[212:215], v151 offset:54272
	ds_read_b128 v[216:219], v151 offset:55296
	ds_read_b128 v[220:223], v151 offset:56320
	global_load_lds_dwordx4 v[156:157], off
	s_add_i32 m0, s34, 0x2000
	s_add_u32 s18, s18, 0x80080
	v_lshl_add_u64 v[156:157], v[192:193], 0, s[30:31]
	s_addc_u32 s19, s19, 0
	s_add_i32 s34, s80, s61
	global_load_lds_dwordx4 v[156:157], off
	v_lshl_add_u64 v[156:157], s[18:19], 0, v[96:97]
	s_mov_b32 m0, s34
	s_nop 0
	global_load_lds_dwordx4 v[156:157], off
	v_lshl_add_u64 v[156:157], s[18:19], 0, v[130:131]
	s_add_i32 m0, s34, 0x2000
	s_nop 0
	global_load_lds_dwordx4 v[156:157], off
	v_lshl_add_u64 v[156:157], v[224:225], 0, s[30:31]
	s_mov_b32 m0, s69
	s_nop 0
	global_load_lds_dwordx4 v[156:157], off
	v_lshl_add_u64 v[156:157], v[226:227], 0, s[30:31]
	s_mov_b32 m0, s70
	s_nop 0
	global_load_lds_dwordx4 v[156:157], off
	s_waitcnt vmcnt(8)
	s_waitcnt lgkmcnt(0)
	s_barrier
	s_waitcnt lgkmcnt(0)
	v_mfma_f32_16x16x32_bf16 v[60:63], v[140:143], v[188:191], v[60:63]
	v_mfma_f32_16x16x32_bf16 v[56:59], v[152:155], v[188:191], v[56:59]
	v_mfma_f32_16x16x32_bf16 v[44:47], v[140:143], v[200:203], v[44:47]
	v_mfma_f32_16x16x32_bf16 v[40:43], v[152:155], v[200:203], v[40:43]
	v_mfma_f32_16x16x32_bf16 v[28:31], v[140:143], v[208:211], v[28:31]
	v_mfma_f32_16x16x32_bf16 v[24:27], v[152:155], v[208:211], v[24:27]
	v_mfma_f32_16x16x32_bf16 v[12:15], v[140:143], v[216:219], v[12:15]
	v_mfma_f32_16x16x32_bf16 v[8:11], v[152:155], v[216:219], v[8:11]
	v_mfma_f32_16x16x32_bf16 v[60:63], v[144:147], v[196:199], v[60:63]
	v_mfma_f32_16x16x32_bf16 v[56:59], v[168:171], v[196:199], v[56:59]
	v_mfma_f32_16x16x32_bf16 v[44:47], v[144:147], v[204:207], v[44:47]
	v_mfma_f32_16x16x32_bf16 v[40:43], v[168:171], v[204:207], v[40:43]
	v_mfma_f32_16x16x32_bf16 v[28:31], v[144:147], v[212:215], v[28:31]
	v_mfma_f32_16x16x32_bf16 v[24:27], v[168:171], v[212:215], v[24:27]
	v_mfma_f32_16x16x32_bf16 v[12:15], v[144:147], v[220:223], v[12:15]
	v_mfma_f32_16x16x32_bf16 v[8:11], v[168:171], v[220:223], v[8:11]
	v_mfma_f32_16x16x32_bf16 v[52:55], v[172:175], v[188:191], v[52:55]
	v_mfma_f32_16x16x32_bf16 v[48:51], v[180:183], v[188:191], v[48:51]
	v_mfma_f32_16x16x32_bf16 v[36:39], v[172:175], v[200:203], v[36:39]
	v_mfma_f32_16x16x32_bf16 v[32:35], v[180:183], v[200:203], v[32:35]
	v_mfma_f32_16x16x32_bf16 v[20:23], v[172:175], v[208:211], v[20:23]
	v_mfma_f32_16x16x32_bf16 v[16:19], v[180:183], v[208:211], v[16:19]
	v_mfma_f32_16x16x32_bf16 v[4:7], v[172:175], v[216:219], v[4:7]
	v_mfma_f32_16x16x32_bf16 v[0:3], v[180:183], v[216:219], v[0:3]
	v_mfma_f32_16x16x32_bf16 v[52:55], v[176:179], v[196:199], v[52:55]
	v_mfma_f32_16x16x32_bf16 v[48:51], v[184:187], v[196:199], v[48:51]
	v_mfma_f32_16x16x32_bf16 v[36:39], v[176:179], v[204:207], v[36:39]
	v_mfma_f32_16x16x32_bf16 v[32:35], v[184:187], v[204:207], v[32:35]
	v_mfma_f32_16x16x32_bf16 v[20:23], v[176:179], v[212:215], v[20:23]
	v_mfma_f32_16x16x32_bf16 v[16:19], v[184:187], v[212:215], v[16:19]
	v_mfma_f32_16x16x32_bf16 v[4:7], v[176:179], v[220:223], v[4:7]
	v_mfma_f32_16x16x32_bf16 v[0:3], v[184:187], v[220:223], v[0:3]
	s_barrier
	s_add_i32 s78, s78, 2
	s_add_u32 s76, s76, 0x100
	s_addc_u32 s77, s77, 0
	s_add_u32 s58, s58, 0x100
	s_addc_u32 s59, s59, 0
	s_cmp_gt_u32 s78, 29
	s_cbranch_scc0 .LBB0_1124
	s_and_b64 vcc, exec, s[24:25]
	s_cbranch_vccz .LBB0_1127
	s_barrier

.LBB0_1198:
	s_add_u32 s18, s48, 0xffe00080
	s_addc_u32 s19, s49, -1
	s_add_i32 s75, 0, 0x10000
	s_cmpk_eq_i32 s74, 0x7c
	s_cselect_b32 s35, s25, s19
	s_cselect_b32 s34, s70, s18
	v_add_u32_e32 v140, s75, v143
	s_cselect_b32 s19, s23, s73
	s_cselect_b32 s18, s71, s72
	s_add_i32 s78, 0, 0x14000
	ds_read_b128 v[146:149], v140
	ds_read_b128 v[150:153], v140 offset:1024
	ds_read_b128 v[154:157], v140 offset:2048
	ds_read_b128 v[168:171], v140 offset:3072
	v_add_u32_e32 v140, s78, v143
	ds_read_b128 v[172:175], v140
	ds_read_b128 v[176:179], v140 offset:1024
	ds_read_b128 v[180:183], v140 offset:2048
	ds_read_b128 v[184:187], v140 offset:3072
	v_lshl_add_u64 v[140:141], s[48:49], 0, v[138:139]
	s_add_i32 m0, s58, 0xc000
	ds_read_b128 v[188:191], v145
	ds_read_b128 v[196:199], v145 offset:1024
	ds_read_b128 v[200:203], v145 offset:2048
	ds_read_b128 v[204:207], v145 offset:3072
	ds_read_b128 v[208:211], v145 offset:4096
	ds_read_b128 v[212:215], v145 offset:5120
	ds_read_b128 v[216:219], v145 offset:6144
	ds_read_b128 v[220:223], v145 offset:7168
	global_load_lds_dwordx4 v[140:141], off
	v_lshl_add_u64 v[140:141], s[48:49], 0, v[136:137]
	s_add_i32 m0, s58, 0xe000
	s_nop 0
	global_load_lds_dwordx4 v[140:141], off
	s_waitcnt vmcnt(8)
	s_waitcnt lgkmcnt(0)
	s_barrier
	s_waitcnt lgkmcnt(0)
	v_mfma_f32_16x16x32_bf16 v[126:129], v[146:149], v[188:191], v[126:129]
	v_mfma_f32_16x16x32_bf16 v[122:125], v[154:157], v[188:191], v[122:125]
	v_mfma_f32_16x16x32_bf16 v[110:113], v[146:149], v[200:203], v[110:113]
	v_mfma_f32_16x16x32_bf16 v[106:109], v[154:157], v[200:203], v[106:109]
	v_mfma_f32_16x16x32_bf16 v[102:105], v[146:149], v[208:211], v[102:105]
	v_mfma_f32_16x16x32_bf16 v[98:101], v[154:157], v[208:211], v[98:101]
	v_mfma_f32_16x16x32_bf16 v[84:87], v[146:149], v[216:219], v[84:87]
	v_mfma_f32_16x16x32_bf16 v[80:83], v[154:157], v[216:219], v[80:83]
	v_mfma_f32_16x16x32_bf16 v[126:129], v[150:153], v[196:199], v[126:129]
	v_mfma_f32_16x16x32_bf16 v[122:125], v[168:171], v[196:199], v[122:125]
	v_mfma_f32_16x16x32_bf16 v[110:113], v[150:153], v[204:207], v[110:113]
	v_mfma_f32_16x16x32_bf16 v[106:109], v[168:171], v[204:207], v[106:109]
	v_mfma_f32_16x16x32_bf16 v[102:105], v[150:153], v[212:215], v[102:105]
	v_mfma_f32_16x16x32_bf16 v[98:101], v[168:171], v[212:215], v[98:101]
	v_mfma_f32_16x16x32_bf16 v[84:87], v[150:153], v[220:223], v[84:87]
	v_mfma_f32_16x16x32_bf16 v[80:83], v[168:171], v[220:223], v[80:83]
	v_mfma_f32_16x16x32_bf16 v[118:121], v[172:175], v[188:191], v[118:121]
	v_mfma_f32_16x16x32_bf16 v[114:117], v[180:183], v[188:191], v[114:117]
	v_mfma_f32_16x16x32_bf16 v[92:95], v[172:175], v[200:203], v[92:95]
	v_mfma_f32_16x16x32_bf16 v[88:91], v[180:183], v[200:203], v[88:91]
	v_mfma_f32_16x16x32_bf16 v[76:79], v[172:175], v[208:211], v[76:79]
	v_mfma_f32_16x16x32_bf16 v[72:75], v[180:183], v[208:211], v[72:75]
	v_mfma_f32_16x16x32_bf16 v[68:71], v[172:175], v[216:219], v[68:71]
	v_mfma_f32_16x16x32_bf16 v[64:67], v[180:183], v[216:219], v[64:67]
	v_mfma_f32_16x16x32_bf16 v[118:121], v[176:179], v[196:199], v[118:121]
	v_mfma_f32_16x16x32_bf16 v[114:117], v[184:187], v[196:199], v[114:117]
	v_mfma_f32_16x16x32_bf16 v[92:95], v[176:179], v[204:207], v[92:95]
	v_mfma_f32_16x16x32_bf16 v[88:91], v[184:187], v[204:207], v[88:91]
	v_mfma_f32_16x16x32_bf16 v[76:79], v[176:179], v[212:215], v[76:79]
	v_mfma_f32_16x16x32_bf16 v[72:75], v[184:187], v[212:215], v[72:75]
	v_mfma_f32_16x16x32_bf16 v[68:71], v[176:179], v[220:223], v[68:71]
	v_mfma_f32_16x16x32_bf16 v[64:67], v[184:187], v[220:223], v[64:67]
	s_barrier
	s_add_i32 s75, s75, s57
	v_lshl_add_u64 v[140:141], s[18:19], 0, v[96:97]
	s_mov_b32 m0, s75
	ds_read_b128 v[188:191], v145 offset:16384
	ds_read_b128 v[196:199], v145 offset:17408
	ds_read_b128 v[200:203], v145 offset:18432
	ds_read_b128 v[204:207], v145 offset:19456
	ds_read_b128 v[208:211], v145 offset:20480
	ds_read_b128 v[212:215], v145 offset:21504
	ds_read_b128 v[216:219], v145 offset:22528
	ds_read_b128 v[220:223], v145 offset:23552
	global_load_lds_dwordx4 v[140:141], off
	s_add_i32 m0, s75, 0x2000
	s_add_u32 s76, s18, 0x200000
	v_lshl_add_u64 v[192:193], s[18:19], 0, v[130:131]
	s_addc_u32 s77, s19, 0
	s_add_i32 s75, s78, s57
	global_load_lds_dwordx4 v[192:193], off
	v_lshl_add_u64 v[224:225], s[76:77], 0, v[96:97]
	s_mov_b32 m0, s75
	v_lshl_add_u64 v[226:227], s[34:35], 0, v[132:133]
	global_load_lds_dwordx4 v[224:225], off
	v_lshl_add_u64 v[224:225], s[76:77], 0, v[130:131]
	s_add_i32 m0, s75, 0x2000
	s_nop 0
	global_load_lds_dwordx4 v[224:225], off
	v_lshl_add_u64 v[224:225], s[34:35], 0, v[134:135]
	s_mov_b32 m0, s58
	s_nop 0
	global_load_lds_dwordx4 v[224:225], off
	s_mov_b32 m0, s59
	s_nop 0
	global_load_lds_dwordx4 v[226:227], off
	s_waitcnt vmcnt(8)
	s_waitcnt lgkmcnt(0)
	s_barrier
	s_waitcnt lgkmcnt(0)
	v_mfma_f32_16x16x32_bf16 v[60:63], v[146:149], v[188:191], v[60:63]
	v_mfma_f32_16x16x32_bf16 v[56:59], v[154:157], v[188:191], v[56:59]
	v_mfma_f32_16x16x32_bf16 v[44:47], v[146:149], v[200:203], v[44:47]
	v_mfma_f32_16x16x32_bf16 v[40:43], v[154:157], v[200:203], v[40:43]
	v_mfma_f32_16x16x32_bf16 v[28:31], v[146:149], v[208:211], v[28:31]
	v_mfma_f32_16x16x32_bf16 v[24:27], v[154:157], v[208:211], v[24:27]
	v_mfma_f32_16x16x32_bf16 v[12:15], v[146:149], v[216:219], v[12:15]
	v_mfma_f32_16x16x32_bf16 v[8:11], v[154:157], v[216:219], v[8:11]
	v_mfma_f32_16x16x32_bf16 v[60:63], v[150:153], v[196:199], v[60:63]
	v_mfma_f32_16x16x32_bf16 v[56:59], v[168:171], v[196:199], v[56:59]
	v_mfma_f32_16x16x32_bf16 v[44:47], v[150:153], v[204:207], v[44:47]
	v_mfma_f32_16x16x32_bf16 v[40:43], v[168:171], v[204:207], v[40:43]
	v_mfma_f32_16x16x32_bf16 v[28:31], v[150:153], v[212:215], v[28:31]
	v_mfma_f32_16x16x32_bf16 v[24:27], v[168:171], v[212:215], v[24:27]
	v_mfma_f32_16x16x32_bf16 v[12:15], v[150:153], v[220:223], v[12:15]
	v_mfma_f32_16x16x32_bf16 v[8:11], v[168:171], v[220:223], v[8:11]
	v_mfma_f32_16x16x32_bf16 v[52:55], v[172:175], v[188:191], v[52:55]
	v_mfma_f32_16x16x32_bf16 v[48:51], v[180:183], v[188:191], v[48:51]
	v_mfma_f32_16x16x32_bf16 v[36:39], v[172:175], v[200:203], v[36:39]
	v_mfma_f32_16x16x32_bf16 v[32:35], v[180:183], v[200:203], v[32:35]
	v_mfma_f32_16x16x32_bf16 v[20:23], v[172:175], v[208:211], v[20:23]
	v_mfma_f32_16x16x32_bf16 v[16:19], v[180:183], v[208:211], v[16:19]
	v_mfma_f32_16x16x32_bf16 v[4:7], v[172:175], v[216:219], v[4:7]
	v_mfma_f32_16x16x32_bf16 v[0:3], v[180:183], v[216:219], v[0:3]
	v_mfma_f32_16x16x32_bf16 v[52:55], v[176:179], v[196:199], v[52:55]
	v_mfma_f32_16x16x32_bf16 v[48:51], v[184:187], v[196:199], v[48:51]
	v_mfma_f32_16x16x32_bf16 v[36:39], v[176:179], v[204:207], v[36:39]
	v_mfma_f32_16x16x32_bf16 v[32:35], v[184:187], v[204:207], v[32:35]
	v_mfma_f32_16x16x32_bf16 v[20:23], v[176:179], v[212:215], v[20:23]
	v_mfma_f32_16x16x32_bf16 v[16:19], v[184:187], v[212:215], v[16:19]
	v_mfma_f32_16x16x32_bf16 v[4:7], v[176:179], v[220:223], v[4:7]
	v_mfma_f32_16x16x32_bf16 v[0:3], v[184:187], v[220:223], v[0:3]
	s_barrier
	s_add_i32 s75, 0, 0x18000
	s_add_i32 s76, 0, 0x1c000
	v_add_u32_e32 v168, s75, v143
	v_add_u32_e32 v184, s76, v143
	ds_read_b128 v[146:149], v168
	ds_read_b128 v[150:153], v168 offset:1024
	ds_read_b128 v[154:157], v168 offset:2048
	ds_read_b128 v[168:171], v168 offset:3072
	ds_read_b128 v[172:175], v184
	ds_read_b128 v[176:179], v184 offset:1024
	ds_read_b128 v[180:183], v184 offset:2048
	ds_read_b128 v[184:187], v184 offset:3072
	s_add_u32 s34, s34, 0x200000
	s_addc_u32 s35, s35, 0
	s_mov_b32 m0, s60
	v_lshl_add_u64 v[228:229], s[34:35], 0, v[134:135]
	ds_read_b128 v[188:191], v145 offset:32768
	ds_read_b128 v[196:199], v145 offset:33792
	ds_read_b128 v[200:203], v145 offset:34816
	ds_read_b128 v[204:207], v145 offset:35840
	ds_read_b128 v[208:211], v145 offset:36864
	ds_read_b128 v[212:215], v145 offset:37888
	ds_read_b128 v[216:219], v145 offset:38912
	ds_read_b128 v[220:223], v145 offset:39936
	global_load_lds_dwordx4 v[228:229], off
	v_lshl_add_u64 v[228:229], s[34:35], 0, v[132:133]
	s_mov_b32 m0, s61
	s_nop 0
	global_load_lds_dwordx4 v[228:229], off
	s_waitcnt vmcnt(8)
	s_waitcnt lgkmcnt(0)
	s_barrier
	s_waitcnt lgkmcnt(0)
	v_mfma_f32_16x16x32_bf16 v[126:129], v[146:149], v[188:191], v[126:129]
	v_mfma_f32_16x16x32_bf16 v[122:125], v[154:157], v[188:191], v[122:125]
	v_mfma_f32_16x16x32_bf16 v[110:113], v[146:149], v[200:203], v[110:113]
	v_mfma_f32_16x16x32_bf16 v[106:109], v[154:157], v[200:203], v[106:109]
	v_mfma_f32_16x16x32_bf16 v[102:105], v[146:149], v[208:211], v[102:105]
	v_mfma_f32_16x16x32_bf16 v[98:101], v[154:157], v[208:211], v[98:101]
	v_mfma_f32_16x16x32_bf16 v[84:87], v[146:149], v[216:219], v[84:87]
	v_mfma_f32_16x16x32_bf16 v[80:83], v[154:157], v[216:219], v[80:83]
	v_mfma_f32_16x16x32_bf16 v[126:129], v[150:153], v[196:199], v[126:129]
	v_mfma_f32_16x16x32_bf16 v[122:125], v[168:171], v[196:199], v[122:125]
	v_mfma_f32_16x16x32_bf16 v[110:113], v[150:153], v[204:207], v[110:113]
	v_mfma_f32_16x16x32_bf16 v[106:109], v[168:171], v[204:207], v[106:109]
	v_mfma_f32_16x16x32_bf16 v[102:105], v[150:153], v[212:215], v[102:105]
	v_mfma_f32_16x16x32_bf16 v[98:101], v[168:171], v[212:215], v[98:101]
	v_mfma_f32_16x16x32_bf16 v[84:87], v[150:153], v[220:223], v[84:87]
	v_mfma_f32_16x16x32_bf16 v[80:83], v[168:171], v[220:223], v[80:83]
	v_mfma_f32_16x16x32_bf16 v[118:121], v[172:175], v[188:191], v[118:121]
	v_mfma_f32_16x16x32_bf16 v[114:117], v[180:183], v[188:191], v[114:117]
	v_mfma_f32_16x16x32_bf16 v[92:95], v[172:175], v[200:203], v[92:95]
	v_mfma_f32_16x16x32_bf16 v[88:91], v[180:183], v[200:203], v[88:91]
	v_mfma_f32_16x16x32_bf16 v[76:79], v[172:175], v[208:211], v[76:79]
	v_mfma_f32_16x16x32_bf16 v[72:75], v[180:183], v[208:211], v[72:75]
	v_mfma_f32_16x16x32_bf16 v[68:71], v[172:175], v[216:219], v[68:71]
	v_mfma_f32_16x16x32_bf16 v[64:67], v[180:183], v[216:219], v[64:67]
	v_mfma_f32_16x16x32_bf16 v[118:121], v[176:179], v[196:199], v[118:121]
	v_mfma_f32_16x16x32_bf16 v[114:117], v[184:187], v[196:199], v[114:117]
	v_mfma_f32_16x16x32_bf16 v[92:95], v[176:179], v[204:207], v[92:95]
	v_mfma_f32_16x16x32_bf16 v[88:91], v[184:187], v[204:207], v[88:91]
	v_mfma_f32_16x16x32_bf16 v[76:79], v[176:179], v[212:215], v[76:79]
	v_mfma_f32_16x16x32_bf16 v[72:75], v[184:187], v[212:215], v[72:75]
	v_mfma_f32_16x16x32_bf16 v[68:71], v[176:179], v[220:223], v[68:71]
	v_mfma_f32_16x16x32_bf16 v[64:67], v[184:187], v[220:223], v[64:67]
	s_barrier
	s_add_i32 s34, s75, s57
	v_lshl_add_u64 v[140:141], v[140:141], 0, s[30:31]
	s_mov_b32 m0, s34
	ds_read_b128 v[188:191], v145 offset:49152
	ds_read_b128 v[196:199], v145 offset:50176
	ds_read_b128 v[200:203], v145 offset:51200
	ds_read_b128 v[204:207], v145 offset:52224
	ds_read_b128 v[208:211], v145 offset:53248
	ds_read_b128 v[212:215], v145 offset:54272
	ds_read_b128 v[216:219], v145 offset:55296
	ds_read_b128 v[220:223], v145 offset:56320
	global_load_lds_dwordx4 v[140:141], off
	s_add_i32 m0, s34, 0x2000
	s_add_u32 s18, s18, 0x200080
	v_lshl_add_u64 v[140:141], v[192:193], 0, s[30:31]
	s_addc_u32 s19, s19, 0
	s_add_i32 s34, s76, s57
	global_load_lds_dwordx4 v[140:141], off
	v_lshl_add_u64 v[140:141], s[18:19], 0, v[96:97]
	s_mov_b32 m0, s34
	s_nop 0
	global_load_lds_dwordx4 v[140:141], off
	v_lshl_add_u64 v[140:141], s[18:19], 0, v[130:131]
	s_add_i32 m0, s34, 0x2000
	s_nop 0
	global_load_lds_dwordx4 v[140:141], off
	v_lshl_add_u64 v[140:141], v[224:225], 0, s[30:31]
	s_mov_b32 m0, s65
	s_nop 0
	global_load_lds_dwordx4 v[140:141], off
	v_lshl_add_u64 v[140:141], v[226:227], 0, s[30:31]
	s_mov_b32 m0, s66
	s_nop 0
	global_load_lds_dwordx4 v[140:141], off
	s_waitcnt vmcnt(8)
	s_waitcnt lgkmcnt(0)
	s_barrier
	s_waitcnt lgkmcnt(0)
	v_mfma_f32_16x16x32_bf16 v[60:63], v[146:149], v[188:191], v[60:63]
	v_mfma_f32_16x16x32_bf16 v[56:59], v[154:157], v[188:191], v[56:59]
	v_mfma_f32_16x16x32_bf16 v[44:47], v[146:149], v[200:203], v[44:47]
	v_mfma_f32_16x16x32_bf16 v[40:43], v[154:157], v[200:203], v[40:43]
	v_mfma_f32_16x16x32_bf16 v[28:31], v[146:149], v[208:211], v[28:31]
	v_mfma_f32_16x16x32_bf16 v[24:27], v[154:157], v[208:211], v[24:27]
	v_mfma_f32_16x16x32_bf16 v[12:15], v[146:149], v[216:219], v[12:15]
	v_mfma_f32_16x16x32_bf16 v[8:11], v[154:157], v[216:219], v[8:11]
	v_mfma_f32_16x16x32_bf16 v[60:63], v[150:153], v[196:199], v[60:63]
	v_mfma_f32_16x16x32_bf16 v[56:59], v[168:171], v[196:199], v[56:59]
	v_mfma_f32_16x16x32_bf16 v[44:47], v[150:153], v[204:207], v[44:47]
	v_mfma_f32_16x16x32_bf16 v[40:43], v[168:171], v[204:207], v[40:43]
	v_mfma_f32_16x16x32_bf16 v[28:31], v[150:153], v[212:215], v[28:31]
	v_mfma_f32_16x16x32_bf16 v[24:27], v[168:171], v[212:215], v[24:27]
	v_mfma_f32_16x16x32_bf16 v[12:15], v[150:153], v[220:223], v[12:15]
	v_mfma_f32_16x16x32_bf16 v[8:11], v[168:171], v[220:223], v[8:11]
	v_mfma_f32_16x16x32_bf16 v[52:55], v[172:175], v[188:191], v[52:55]
	v_mfma_f32_16x16x32_bf16 v[48:51], v[180:183], v[188:191], v[48:51]
	v_mfma_f32_16x16x32_bf16 v[36:39], v[172:175], v[200:203], v[36:39]
	v_mfma_f32_16x16x32_bf16 v[32:35], v[180:183], v[200:203], v[32:35]
	v_mfma_f32_16x16x32_bf16 v[20:23], v[172:175], v[208:211], v[20:23]
	v_mfma_f32_16x16x32_bf16 v[16:19], v[180:183], v[208:211], v[16:19]
	v_mfma_f32_16x16x32_bf16 v[4:7], v[172:175], v[216:219], v[4:7]
	v_mfma_f32_16x16x32_bf16 v[0:3], v[180:183], v[216:219], v[0:3]
	v_mfma_f32_16x16x32_bf16 v[52:55], v[176:179], v[196:199], v[52:55]
	v_mfma_f32_16x16x32_bf16 v[48:51], v[184:187], v[196:199], v[48:51]
	v_mfma_f32_16x16x32_bf16 v[36:39], v[176:179], v[204:207], v[36:39]
	v_mfma_f32_16x16x32_bf16 v[32:35], v[184:187], v[204:207], v[32:35]
	v_mfma_f32_16x16x32_bf16 v[20:23], v[176:179], v[212:215], v[20:23]
	v_mfma_f32_16x16x32_bf16 v[16:19], v[184:187], v[212:215], v[16:19]
	v_mfma_f32_16x16x32_bf16 v[4:7], v[176:179], v[220:223], v[4:7]
	v_mfma_f32_16x16x32_bf16 v[0:3], v[184:187], v[220:223], v[0:3]
	s_barrier
	s_add_i32 s74, s74, 2
	s_add_u32 s72, s72, 0x100
	s_addc_u32 s73, s73, 0
	s_add_u32 s48, s48, 0x100
	s_addc_u32 s49, s49, 0
	s_cmpk_gt_u32 s74, 0x7d
	s_cbranch_scc0 .LBB0_1198
	s_and_b64 vcc, exec, s[14:15]
	s_cbranch_vccz .LBB0_1201
	s_barrier

.LBB0_1327:
	s_add_u32 s18, s42, 0xffe00080
	s_addc_u32 s19, s43, -1
	s_add_i32 s83, 0, 0x10000
	s_cmpk_eq_i32 s82, 0x7c
	s_cselect_b32 s61, s25, s19
	s_cselect_b32 s60, s78, s18
	s_cselect_b32 s19, s49, s81
	s_cselect_b32 s18, s79, s80
	s_add_i32 s86, 0, 0x14000
	v_add_u32_e32 v152, s83, v201
	v_add_u32_e32 v156, s86, v201
	ds_read_b128 v[140:143], v152
	ds_read_b128 v[144:147], v152 offset:1024
	ds_read_b128 v[148:151], v152 offset:2048
	ds_read_b128 v[152:155], v152 offset:3072
	ds_read_b128 v[168:171], v156
	ds_read_b128 v[172:175], v156 offset:1024
	ds_read_b128 v[176:179], v156 offset:2048
	ds_read_b128 v[180:183], v156 offset:3072
	v_lshl_add_u64 v[156:157], s[42:43], 0, v[138:139]
	s_add_i32 m0, s68, 0xc000
	ds_read_b128 v[184:187], v205
	ds_read_b128 v[188:191], v205 offset:1024
	ds_read_b128 v[196:199], v205 offset:2048
	ds_read_b128 v[206:209], v205 offset:3072
	ds_read_b128 v[210:213], v205 offset:4096
	ds_read_b128 v[214:217], v205 offset:5120
	ds_read_b128 v[218:221], v205 offset:6144
	ds_read_b128 v[222:225], v205 offset:7168
	global_load_lds_dwordx4 v[156:157], off
	v_lshl_add_u64 v[156:157], s[42:43], 0, v[136:137]
	s_add_i32 m0, s68, 0xe000
	s_nop 0
	global_load_lds_dwordx4 v[156:157], off
	s_waitcnt vmcnt(8)
	s_waitcnt lgkmcnt(0)
	s_barrier
	s_waitcnt lgkmcnt(0)
	v_mfma_f32_16x16x32_bf16 v[126:129], v[140:143], v[184:187], v[126:129]
	v_mfma_f32_16x16x32_bf16 v[122:125], v[148:151], v[184:187], v[122:125]
	v_mfma_f32_16x16x32_bf16 v[110:113], v[140:143], v[196:199], v[110:113]
	v_mfma_f32_16x16x32_bf16 v[106:109], v[148:151], v[196:199], v[106:109]
	v_mfma_f32_16x16x32_bf16 v[92:95], v[140:143], v[210:213], v[92:95]
	v_mfma_f32_16x16x32_bf16 v[88:91], v[148:151], v[210:213], v[88:91]
	v_mfma_f32_16x16x32_bf16 v[76:79], v[140:143], v[218:221], v[76:79]
	v_mfma_f32_16x16x32_bf16 v[72:75], v[148:151], v[218:221], v[72:75]
	v_mfma_f32_16x16x32_bf16 v[126:129], v[144:147], v[188:191], v[126:129]
	v_mfma_f32_16x16x32_bf16 v[122:125], v[152:155], v[188:191], v[122:125]
	v_mfma_f32_16x16x32_bf16 v[110:113], v[144:147], v[206:209], v[110:113]
	v_mfma_f32_16x16x32_bf16 v[106:109], v[152:155], v[206:209], v[106:109]
	v_mfma_f32_16x16x32_bf16 v[92:95], v[144:147], v[214:217], v[92:95]
	v_mfma_f32_16x16x32_bf16 v[88:91], v[152:155], v[214:217], v[88:91]
	v_mfma_f32_16x16x32_bf16 v[76:79], v[144:147], v[222:225], v[76:79]
	v_mfma_f32_16x16x32_bf16 v[72:75], v[152:155], v[222:225], v[72:75]
	v_mfma_f32_16x16x32_bf16 v[118:121], v[168:171], v[184:187], v[118:121]
	v_mfma_f32_16x16x32_bf16 v[114:117], v[176:179], v[184:187], v[114:117]
	v_mfma_f32_16x16x32_bf16 v[102:105], v[168:171], v[196:199], v[102:105]
	v_mfma_f32_16x16x32_bf16 v[98:101], v[176:179], v[196:199], v[98:101]
	v_mfma_f32_16x16x32_bf16 v[84:87], v[168:171], v[210:213], v[84:87]
	v_mfma_f32_16x16x32_bf16 v[80:83], v[176:179], v[210:213], v[80:83]
	v_mfma_f32_16x16x32_bf16 v[68:71], v[168:171], v[218:221], v[68:71]
	v_mfma_f32_16x16x32_bf16 v[64:67], v[176:179], v[218:221], v[64:67]
	v_mfma_f32_16x16x32_bf16 v[118:121], v[172:175], v[188:191], v[118:121]
	v_mfma_f32_16x16x32_bf16 v[114:117], v[180:183], v[188:191], v[114:117]
	v_mfma_f32_16x16x32_bf16 v[102:105], v[172:175], v[206:209], v[102:105]
	v_mfma_f32_16x16x32_bf16 v[98:101], v[180:183], v[206:209], v[98:101]
	v_mfma_f32_16x16x32_bf16 v[84:87], v[172:175], v[214:217], v[84:87]
	v_mfma_f32_16x16x32_bf16 v[80:83], v[180:183], v[214:217], v[80:83]
	v_mfma_f32_16x16x32_bf16 v[68:71], v[172:175], v[222:225], v[68:71]
	v_mfma_f32_16x16x32_bf16 v[64:67], v[180:183], v[222:225], v[64:67]
	s_barrier
	s_add_i32 s83, s83, s67
	v_lshl_add_u64 v[156:157], s[18:19], 0, v[96:97]
	s_mov_b32 m0, s83
	ds_read_b128 v[184:187], v205 offset:16384
	ds_read_b128 v[188:191], v205 offset:17408
	ds_read_b128 v[196:199], v205 offset:18432
	ds_read_b128 v[206:209], v205 offset:19456
	ds_read_b128 v[210:213], v205 offset:20480
	ds_read_b128 v[214:217], v205 offset:21504
	ds_read_b128 v[218:221], v205 offset:22528
	ds_read_b128 v[222:225], v205 offset:23552
	global_load_lds_dwordx4 v[156:157], off
	s_add_i32 m0, s83, 0x2000
	s_add_u32 s84, s18, 0x200000
	v_lshl_add_u64 v[192:193], s[18:19], 0, v[130:131]
	s_addc_u32 s85, s19, 0
	s_add_i32 s83, s86, s67
	global_load_lds_dwordx4 v[192:193], off
	v_lshl_add_u64 v[226:227], s[84:85], 0, v[96:97]
	s_mov_b32 m0, s83
	v_lshl_add_u64 v[228:229], s[60:61], 0, v[132:133]
	global_load_lds_dwordx4 v[226:227], off
	v_lshl_add_u64 v[226:227], s[84:85], 0, v[130:131]
	s_add_i32 m0, s83, 0x2000
	s_nop 0
	global_load_lds_dwordx4 v[226:227], off
	v_lshl_add_u64 v[226:227], s[60:61], 0, v[134:135]
	s_mov_b32 m0, s68
	s_nop 0
	global_load_lds_dwordx4 v[226:227], off
	s_mov_b32 m0, s69
	s_nop 0
	global_load_lds_dwordx4 v[228:229], off
	s_waitcnt vmcnt(8)
	s_waitcnt lgkmcnt(0)
	s_barrier
	s_waitcnt lgkmcnt(0)
	v_mfma_f32_16x16x32_bf16 v[60:63], v[140:143], v[184:187], v[60:63]
	v_mfma_f32_16x16x32_bf16 v[56:59], v[148:151], v[184:187], v[56:59]
	v_mfma_f32_16x16x32_bf16 v[44:47], v[140:143], v[196:199], v[44:47]
	v_mfma_f32_16x16x32_bf16 v[40:43], v[148:151], v[196:199], v[40:43]
	v_mfma_f32_16x16x32_bf16 v[28:31], v[140:143], v[210:213], v[28:31]
	v_mfma_f32_16x16x32_bf16 v[24:27], v[148:151], v[210:213], v[24:27]
	v_mfma_f32_16x16x32_bf16 v[12:15], v[140:143], v[218:221], v[12:15]
	v_mfma_f32_16x16x32_bf16 v[8:11], v[148:151], v[218:221], v[8:11]
	v_mfma_f32_16x16x32_bf16 v[60:63], v[144:147], v[188:191], v[60:63]
	v_mfma_f32_16x16x32_bf16 v[56:59], v[152:155], v[188:191], v[56:59]
	v_mfma_f32_16x16x32_bf16 v[44:47], v[144:147], v[206:209], v[44:47]
	v_mfma_f32_16x16x32_bf16 v[40:43], v[152:155], v[206:209], v[40:43]
	v_mfma_f32_16x16x32_bf16 v[28:31], v[144:147], v[214:217], v[28:31]
	v_mfma_f32_16x16x32_bf16 v[24:27], v[152:155], v[214:217], v[24:27]
	v_mfma_f32_16x16x32_bf16 v[12:15], v[144:147], v[222:225], v[12:15]
	v_mfma_f32_16x16x32_bf16 v[8:11], v[152:155], v[222:225], v[8:11]
	v_mfma_f32_16x16x32_bf16 v[52:55], v[168:171], v[184:187], v[52:55]
	v_mfma_f32_16x16x32_bf16 v[48:51], v[176:179], v[184:187], v[48:51]
	v_mfma_f32_16x16x32_bf16 v[36:39], v[168:171], v[196:199], v[36:39]
	v_mfma_f32_16x16x32_bf16 v[32:35], v[176:179], v[196:199], v[32:35]
	v_mfma_f32_16x16x32_bf16 v[20:23], v[168:171], v[210:213], v[20:23]
	v_mfma_f32_16x16x32_bf16 v[16:19], v[176:179], v[210:213], v[16:19]
	v_mfma_f32_16x16x32_bf16 v[4:7], v[168:171], v[218:221], v[4:7]
	v_mfma_f32_16x16x32_bf16 v[0:3], v[176:179], v[218:221], v[0:3]
	v_mfma_f32_16x16x32_bf16 v[52:55], v[172:175], v[188:191], v[52:55]
	v_mfma_f32_16x16x32_bf16 v[48:51], v[180:183], v[188:191], v[48:51]
	v_mfma_f32_16x16x32_bf16 v[36:39], v[172:175], v[206:209], v[36:39]
	v_mfma_f32_16x16x32_bf16 v[32:35], v[180:183], v[206:209], v[32:35]
	v_mfma_f32_16x16x32_bf16 v[20:23], v[172:175], v[214:217], v[20:23]
	v_mfma_f32_16x16x32_bf16 v[16:19], v[180:183], v[214:217], v[16:19]
	v_mfma_f32_16x16x32_bf16 v[4:7], v[172:175], v[222:225], v[4:7]
	v_mfma_f32_16x16x32_bf16 v[0:3], v[180:183], v[222:225], v[0:3]
	s_barrier
	s_add_i32 s83, 0, 0x18000
	s_add_i32 s84, 0, 0x1c000
	v_add_u32_e32 v152, s83, v201
	v_add_u32_e32 v180, s84, v201
	ds_read_b128 v[140:143], v152
	ds_read_b128 v[144:147], v152 offset:1024
	ds_read_b128 v[148:151], v152 offset:2048
	ds_read_b128 v[152:155], v152 offset:3072
	ds_read_b128 v[168:171], v180
	ds_read_b128 v[172:175], v180 offset:1024
	ds_read_b128 v[176:179], v180 offset:2048
	ds_read_b128 v[180:183], v180 offset:3072
	s_add_u32 s60, s60, 0x200000
	s_addc_u32 s61, s61, 0
	s_mov_b32 m0, s70
	v_lshl_add_u64 v[230:231], s[60:61], 0, v[134:135]
	ds_read_b128 v[184:187], v205 offset:32768
	ds_read_b128 v[188:191], v205 offset:33792
	ds_read_b128 v[196:199], v205 offset:34816
	ds_read_b128 v[206:209], v205 offset:35840
	ds_read_b128 v[210:213], v205 offset:36864
	ds_read_b128 v[214:217], v205 offset:37888
	ds_read_b128 v[218:221], v205 offset:38912
	ds_read_b128 v[222:225], v205 offset:39936
	global_load_lds_dwordx4 v[230:231], off
	v_lshl_add_u64 v[230:231], s[60:61], 0, v[132:133]
	s_mov_b32 m0, s71
	s_nop 0
	global_load_lds_dwordx4 v[230:231], off
	s_waitcnt vmcnt(8)
	s_waitcnt lgkmcnt(0)
	s_barrier
	s_waitcnt lgkmcnt(0)
	v_mfma_f32_16x16x32_bf16 v[126:129], v[140:143], v[184:187], v[126:129]
	v_mfma_f32_16x16x32_bf16 v[122:125], v[148:151], v[184:187], v[122:125]
	v_mfma_f32_16x16x32_bf16 v[110:113], v[140:143], v[196:199], v[110:113]
	v_mfma_f32_16x16x32_bf16 v[106:109], v[148:151], v[196:199], v[106:109]
	v_mfma_f32_16x16x32_bf16 v[92:95], v[140:143], v[210:213], v[92:95]
	v_mfma_f32_16x16x32_bf16 v[88:91], v[148:151], v[210:213], v[88:91]
	v_mfma_f32_16x16x32_bf16 v[76:79], v[140:143], v[218:221], v[76:79]
	v_mfma_f32_16x16x32_bf16 v[72:75], v[148:151], v[218:221], v[72:75]
	v_mfma_f32_16x16x32_bf16 v[126:129], v[144:147], v[188:191], v[126:129]
	v_mfma_f32_16x16x32_bf16 v[122:125], v[152:155], v[188:191], v[122:125]
	v_mfma_f32_16x16x32_bf16 v[110:113], v[144:147], v[206:209], v[110:113]
	v_mfma_f32_16x16x32_bf16 v[106:109], v[152:155], v[206:209], v[106:109]
	v_mfma_f32_16x16x32_bf16 v[92:95], v[144:147], v[214:217], v[92:95]
	v_mfma_f32_16x16x32_bf16 v[88:91], v[152:155], v[214:217], v[88:91]
	v_mfma_f32_16x16x32_bf16 v[76:79], v[144:147], v[222:225], v[76:79]
	v_mfma_f32_16x16x32_bf16 v[72:75], v[152:155], v[222:225], v[72:75]
	v_mfma_f32_16x16x32_bf16 v[118:121], v[168:171], v[184:187], v[118:121]
	v_mfma_f32_16x16x32_bf16 v[114:117], v[176:179], v[184:187], v[114:117]
	v_mfma_f32_16x16x32_bf16 v[102:105], v[168:171], v[196:199], v[102:105]
	v_mfma_f32_16x16x32_bf16 v[98:101], v[176:179], v[196:199], v[98:101]
	v_mfma_f32_16x16x32_bf16 v[84:87], v[168:171], v[210:213], v[84:87]
	v_mfma_f32_16x16x32_bf16 v[80:83], v[176:179], v[210:213], v[80:83]
	v_mfma_f32_16x16x32_bf16 v[68:71], v[168:171], v[218:221], v[68:71]
	v_mfma_f32_16x16x32_bf16 v[64:67], v[176:179], v[218:221], v[64:67]
	v_mfma_f32_16x16x32_bf16 v[118:121], v[172:175], v[188:191], v[118:121]
	v_mfma_f32_16x16x32_bf16 v[114:117], v[180:183], v[188:191], v[114:117]
	v_mfma_f32_16x16x32_bf16 v[102:105], v[172:175], v[206:209], v[102:105]
	v_mfma_f32_16x16x32_bf16 v[98:101], v[180:183], v[206:209], v[98:101]
	v_mfma_f32_16x16x32_bf16 v[84:87], v[172:175], v[214:217], v[84:87]
	v_mfma_f32_16x16x32_bf16 v[80:83], v[180:183], v[214:217], v[80:83]
	v_mfma_f32_16x16x32_bf16 v[68:71], v[172:175], v[222:225], v[68:71]
	v_mfma_f32_16x16x32_bf16 v[64:67], v[180:183], v[222:225], v[64:67]
	s_barrier
	s_add_i32 s60, s83, s67
	v_lshl_add_u64 v[156:157], v[156:157], 0, s[30:31]
	s_mov_b32 m0, s60
	ds_read_b128 v[184:187], v205 offset:49152
	ds_read_b128 v[188:191], v205 offset:50176
	ds_read_b128 v[196:199], v205 offset:51200
	ds_read_b128 v[206:209], v205 offset:52224
	ds_read_b128 v[210:213], v205 offset:53248
	ds_read_b128 v[214:217], v205 offset:54272
	ds_read_b128 v[218:221], v205 offset:55296
	ds_read_b128 v[222:225], v205 offset:56320
	global_load_lds_dwordx4 v[156:157], off
	s_add_i32 m0, s60, 0x2000
	s_add_u32 s18, s18, 0x200080
	v_lshl_add_u64 v[156:157], v[192:193], 0, s[30:31]
	s_addc_u32 s19, s19, 0
	s_add_i32 s60, s84, s67
	global_load_lds_dwordx4 v[156:157], off
	v_lshl_add_u64 v[156:157], s[18:19], 0, v[96:97]
	s_mov_b32 m0, s60
	s_nop 0
	global_load_lds_dwordx4 v[156:157], off
	v_lshl_add_u64 v[156:157], s[18:19], 0, v[130:131]
	s_add_i32 m0, s60, 0x2000
	s_nop 0
	global_load_lds_dwordx4 v[156:157], off
	v_lshl_add_u64 v[156:157], v[226:227], 0, s[30:31]
	s_mov_b32 m0, s74
	s_nop 0
	global_load_lds_dwordx4 v[156:157], off
	v_lshl_add_u64 v[156:157], v[228:229], 0, s[30:31]
	s_mov_b32 m0, s75
	s_nop 0
	global_load_lds_dwordx4 v[156:157], off
	s_waitcnt vmcnt(8)
	s_waitcnt lgkmcnt(0)
	s_barrier
	s_waitcnt lgkmcnt(0)
	v_mfma_f32_16x16x32_bf16 v[60:63], v[140:143], v[184:187], v[60:63]
	v_mfma_f32_16x16x32_bf16 v[56:59], v[148:151], v[184:187], v[56:59]
	v_mfma_f32_16x16x32_bf16 v[44:47], v[140:143], v[196:199], v[44:47]
	v_mfma_f32_16x16x32_bf16 v[40:43], v[148:151], v[196:199], v[40:43]
	v_mfma_f32_16x16x32_bf16 v[28:31], v[140:143], v[210:213], v[28:31]
	v_mfma_f32_16x16x32_bf16 v[24:27], v[148:151], v[210:213], v[24:27]
	v_mfma_f32_16x16x32_bf16 v[12:15], v[140:143], v[218:221], v[12:15]
	v_mfma_f32_16x16x32_bf16 v[8:11], v[148:151], v[218:221], v[8:11]
	v_mfma_f32_16x16x32_bf16 v[60:63], v[144:147], v[188:191], v[60:63]
	v_mfma_f32_16x16x32_bf16 v[56:59], v[152:155], v[188:191], v[56:59]
	v_mfma_f32_16x16x32_bf16 v[44:47], v[144:147], v[206:209], v[44:47]
	v_mfma_f32_16x16x32_bf16 v[40:43], v[152:155], v[206:209], v[40:43]
	v_mfma_f32_16x16x32_bf16 v[28:31], v[144:147], v[214:217], v[28:31]
	v_mfma_f32_16x16x32_bf16 v[24:27], v[152:155], v[214:217], v[24:27]
	v_mfma_f32_16x16x32_bf16 v[12:15], v[144:147], v[222:225], v[12:15]
	v_mfma_f32_16x16x32_bf16 v[8:11], v[152:155], v[222:225], v[8:11]
	v_mfma_f32_16x16x32_bf16 v[52:55], v[168:171], v[184:187], v[52:55]
	v_mfma_f32_16x16x32_bf16 v[48:51], v[176:179], v[184:187], v[48:51]
	v_mfma_f32_16x16x32_bf16 v[36:39], v[168:171], v[196:199], v[36:39]
	v_mfma_f32_16x16x32_bf16 v[32:35], v[176:179], v[196:199], v[32:35]
	v_mfma_f32_16x16x32_bf16 v[20:23], v[168:171], v[210:213], v[20:23]
	v_mfma_f32_16x16x32_bf16 v[16:19], v[176:179], v[210:213], v[16:19]
	v_mfma_f32_16x16x32_bf16 v[4:7], v[168:171], v[218:221], v[4:7]
	v_mfma_f32_16x16x32_bf16 v[0:3], v[176:179], v[218:221], v[0:3]
	v_mfma_f32_16x16x32_bf16 v[52:55], v[172:175], v[188:191], v[52:55]
	v_mfma_f32_16x16x32_bf16 v[48:51], v[180:183], v[188:191], v[48:51]
	v_mfma_f32_16x16x32_bf16 v[36:39], v[172:175], v[206:209], v[36:39]
	v_mfma_f32_16x16x32_bf16 v[32:35], v[180:183], v[206:209], v[32:35]
	v_mfma_f32_16x16x32_bf16 v[20:23], v[172:175], v[214:217], v[20:23]
	v_mfma_f32_16x16x32_bf16 v[16:19], v[180:183], v[214:217], v[16:19]
	v_mfma_f32_16x16x32_bf16 v[4:7], v[172:175], v[222:225], v[4:7]
	v_mfma_f32_16x16x32_bf16 v[0:3], v[180:183], v[222:225], v[0:3]
	s_barrier
	s_add_i32 s82, s82, 2
	s_add_u32 s80, s80, 0x100
	s_addc_u32 s81, s81, 0
	s_add_u32 s42, s42, 0x100
	s_addc_u32 s43, s43, 0
	s_cmpk_gt_u32 s82, 0x7d
	s_cbranch_scc0 .LBB0_1327
	s_and_b64 vcc, exec, s[22:23]
	s_cbranch_vccz .LBB0_1330
	s_barrier
